# add hand-written GLU epilogue (biases first, z and gate rows requested 3 rounds ahead), K-loop placement pads
# speedup vs baseline: 1.0042x; 1.0042x over previous
.Lpb_next:
	s_add_i32 s65, s65, s3
	s_cmpk_lt_i32 s65, 0x440
	s_cbranch_scc1 .Lpb_loop
	s_branch .LBB0_178
	s_nop 0
	s_nop 0
	s_nop 0
	s_nop 0
	s_nop 0
	s_nop 0
	s_nop 0
	s_nop 0
	s_nop 0
	s_nop 0
	s_nop 0
	s_nop 0
	s_nop 0
	s_nop 0
	s_nop 0
	s_nop 0
	s_nop 0
	s_nop 0
	s_nop 0
	s_nop 0
	s_nop 0
	s_branch .LBB0_178
	s_nop 0
	s_nop 0
	s_nop 0
	s_nop 0
	s_nop 0
	s_nop 0
	s_nop 0
	s_nop 0
	s_nop 0
	s_nop 0
	s_nop 0
	s_nop 0
	s_nop 0
	s_nop 0
	s_nop 0
	s_nop 0
	s_nop 0
	s_nop 0
	s_nop 0
	s_nop 0
	s_nop 0
	s_nop 0
	s_nop 0
	s_nop 0
	s_nop 0
	s_nop 0
	s_nop 0
	s_nop 0
	s_nop 0
	s_nop 0
	s_nop 0
	s_nop 0
	s_nop 0
	s_nop 0
	s_nop 0
	s_nop 0
	s_nop 0
	s_nop 0
	s_nop 0
	s_nop 0
	s_nop 0
	s_nop 0
	s_nop 0
	s_nop 0
	s_nop 0
	s_nop 0
	s_nop 0
	s_nop 0
	s_nop 0
	s_nop 0
	s_nop 0
	s_nop 0
	s_nop 0
	s_nop 0
	s_nop 0
	s_nop 0
	s_nop 0
	s_nop 0
	s_nop 0
	s_nop 0
	s_nop 0
	s_nop 0
	s_nop 0

.LBB0_695:
	v_lshl_add_u32 v148, s6, 8, v150
	s_lshl_b32 s0, s4, 8
	v_or_b32_e32 v149, s0, v152
	v_mov_b32_e32 v181, 0
	v_lshlrev_b32_e32 v180, 11, v148
	v_lshl_add_u32 v180, v149, 1, v180
	v_lshl_add_u64 v[142:143], s[40:41], 0, v[180:181]
	v_lshlrev_b32_e32 v180, 2, v149
	v_lshl_add_u64 v[178:179], s[46:47], 0, v[180:181]
	global_load_dwordx4 v[154:157], v[178:179], off
	global_load_dwordx4 v[158:161], v[178:179], off offset:16
	global_load_dwordx4 v[162:165], v[178:179], off offset:512
	global_load_dwordx4 v[166:169], v[178:179], off offset:528
	s_add_i32 s4, s0, 0x2400
	s_ashr_i32 s0, s4, 9
	s_mul_hi_i32 s4, s0, 0x1100000
	s_mul_i32 s0, s0, 0x1100000
	s_add_u32 s58, s65, s0
	s_addc_u32 s59, s66, s4
	v_and_b32_e32 v180, 0x1ff, v149
	v_lshlrev_b32_e32 v180, 1, v180
	v_lshl_add_u32 v180, v148, 10, v180
	v_lshl_add_u64 v[144:145], s[58:59], 0, v[180:181]
	v_lshlrev_b32_e32 v180, 13, v148
	v_lshl_add_u32 v180, v149, 1, v180
	v_add_u32_e32 v180, 0x1000, v180
	v_lshl_add_u64 v[146:147], s[44:45], 0, v[180:181]
	global_load_dwordx4 v[170:173], v[142:143], off
	global_load_dwordx4 v[174:177], v[144:145], off
	s_waitcnt vmcnt(2)
	v_pk_add_f32 v[126:127], v[126:127], v[154:155]
	v_pk_add_f32 v[122:123], v[122:123], v[158:159]
	v_pk_add_f32 v[128:129], v[128:129], v[156:157]
	v_pk_add_f32 v[124:125], v[124:125], v[160:161]
	v_pk_add_f32 v[118:119], v[118:119], v[162:163]
	v_pk_add_f32 v[114:115], v[114:115], v[166:167]
	v_pk_add_f32 v[120:121], v[120:121], v[164:165]
	v_pk_add_f32 v[116:117], v[116:117], v[168:169]
	v_pk_add_f32 v[110:111], v[110:111], v[154:155]
	v_pk_add_f32 v[106:107], v[106:107], v[158:159]
	v_pk_add_f32 v[112:113], v[112:113], v[156:157]
	v_pk_add_f32 v[108:109], v[108:109], v[160:161]
	v_pk_add_f32 v[102:103], v[102:103], v[162:163]
	v_pk_add_f32 v[98:99], v[98:99], v[166:167]
	v_pk_add_f32 v[104:105], v[104:105], v[164:165]
	v_pk_add_f32 v[100:101], v[100:101], v[168:169]
	v_pk_add_f32 v[94:95], v[94:95], v[154:155]
	v_pk_add_f32 v[90:91], v[90:91], v[158:159]
	v_pk_add_f32 v[96:97], v[96:97], v[156:157]
	v_pk_add_f32 v[92:93], v[92:93], v[160:161]
	v_pk_add_f32 v[86:87], v[86:87], v[162:163]
	v_pk_add_f32 v[82:83], v[82:83], v[166:167]
	v_pk_add_f32 v[88:89], v[88:89], v[164:165]
	v_pk_add_f32 v[84:85], v[84:85], v[168:169]
	v_pk_add_f32 v[78:79], v[78:79], v[154:155]
	v_pk_add_f32 v[74:75], v[74:75], v[158:159]
	v_pk_add_f32 v[80:81], v[80:81], v[156:157]
	v_pk_add_f32 v[76:77], v[76:77], v[160:161]
	v_pk_add_f32 v[70:71], v[70:71], v[162:163]
	v_pk_add_f32 v[66:67], v[66:67], v[166:167]
	v_pk_add_f32 v[72:73], v[72:73], v[164:165]
	v_pk_add_f32 v[68:69], v[68:69], v[168:169]
	v_pk_add_f32 v[62:63], v[62:63], v[154:155]
	v_pk_add_f32 v[58:59], v[58:59], v[158:159]
	v_pk_add_f32 v[64:65], v[64:65], v[156:157]
	v_pk_add_f32 v[60:61], v[60:61], v[160:161]
	v_pk_add_f32 v[54:55], v[54:55], v[162:163]
	v_pk_add_f32 v[50:51], v[50:51], v[166:167]
	v_pk_add_f32 v[56:57], v[56:57], v[164:165]
	v_pk_add_f32 v[52:53], v[52:53], v[168:169]
	v_pk_add_f32 v[46:47], v[46:47], v[154:155]
	v_pk_add_f32 v[42:43], v[42:43], v[158:159]
	v_pk_add_f32 v[48:49], v[48:49], v[156:157]
	v_pk_add_f32 v[44:45], v[44:45], v[160:161]
	v_pk_add_f32 v[38:39], v[38:39], v[162:163]
	v_pk_add_f32 v[34:35], v[34:35], v[166:167]
	v_pk_add_f32 v[40:41], v[40:41], v[164:165]
	v_pk_add_f32 v[36:37], v[36:37], v[168:169]
	v_pk_add_f32 v[30:31], v[30:31], v[154:155]
	v_pk_add_f32 v[26:27], v[26:27], v[158:159]
	v_pk_add_f32 v[32:33], v[32:33], v[156:157]
	v_pk_add_f32 v[28:29], v[28:29], v[160:161]
	v_pk_add_f32 v[22:23], v[22:23], v[162:163]
	v_pk_add_f32 v[18:19], v[18:19], v[166:167]
	v_pk_add_f32 v[24:25], v[24:25], v[164:165]
	v_pk_add_f32 v[20:21], v[20:21], v[168:169]
	v_pk_add_f32 v[14:15], v[14:15], v[154:155]
	v_pk_add_f32 v[10:11], v[10:11], v[158:159]
	v_pk_add_f32 v[16:17], v[16:17], v[156:157]
	v_pk_add_f32 v[12:13], v[12:13], v[160:161]
	v_pk_add_f32 v[6:7], v[6:7], v[162:163]
	v_pk_add_f32 v[2:3], v[2:3], v[166:167]
	v_pk_add_f32 v[8:9], v[8:9], v[164:165]
	v_pk_add_f32 v[4:5], v[4:5], v[168:169]
	global_load_dwordx4 v[154:157], v[142:143], off offset:256
	global_load_dwordx4 v[158:161], v[144:145], off offset:256
	s_mov_b64 s[58:59], 0x8000
	v_lshl_add_u64 v[142:143], v[142:143], 0, s[58:59]
	s_mov_b64 s[58:59], 0x4000
	v_lshl_add_u64 v[144:145], v[144:145], 0, s[58:59]
	global_load_dwordx4 v[162:165], v[142:143], off
	global_load_dwordx4 v[166:169], v[144:145], off
	s_waitcnt vmcnt(4)
	v_lshlrev_b32_e32 v178, 16, v170
	v_and_b32_e32 v170, 0xffff0000, v170
	v_lshlrev_b32_e32 v179, 16, v174
	v_and_b32_e32 v174, 0xffff0000, v174
	v_mul_f32_e32 v126, 0xbfb8aa3b, v126
	v_mul_f32_e32 v127, 0xbfb8aa3b, v127
	v_mul_f32_e32 v180, 0xbfb8aa3b, v179
	v_mul_f32_e32 v181, 0xbfb8aa3b, v174
	v_exp_f32_e32 v126, v126
	v_exp_f32_e32 v127, v127
	v_exp_f32_e32 v180, v180
	v_exp_f32_e32 v181, v181
	v_add_f32_e32 v126, 1.0, v126
	v_add_f32_e32 v127, 1.0, v127
	v_add_f32_e32 v180, 1.0, v180
	v_add_f32_e32 v181, 1.0, v181
	v_rcp_f32_e32 v126, v126
	v_rcp_f32_e32 v127, v127
	v_rcp_f32_e32 v180, v180
	v_rcp_f32_e32 v181, v181
	v_mul_f32_e32 v126, v126, v178
	v_mul_f32_e32 v127, v127, v170
	v_mul_f32_e32 v180, v180, v179
	v_mul_f32_e32 v181, v181, v174
	v_mul_f32_e32 v126, v126, v180
	v_mul_f32_e32 v127, v127, v181
	v_lshlrev_b32_e32 v178, 16, v171
	v_and_b32_e32 v171, 0xffff0000, v171
	v_lshlrev_b32_e32 v179, 16, v175
	v_and_b32_e32 v175, 0xffff0000, v175
	v_mul_f32_e32 v128, 0xbfb8aa3b, v128
	v_mul_f32_e32 v129, 0xbfb8aa3b, v129
	v_mul_f32_e32 v180, 0xbfb8aa3b, v179
	v_mul_f32_e32 v181, 0xbfb8aa3b, v175
	v_exp_f32_e32 v128, v128
	v_exp_f32_e32 v129, v129
	v_exp_f32_e32 v180, v180
	v_exp_f32_e32 v181, v181
	v_add_f32_e32 v128, 1.0, v128
	v_add_f32_e32 v129, 1.0, v129
	v_add_f32_e32 v180, 1.0, v180
	v_add_f32_e32 v181, 1.0, v181
	v_rcp_f32_e32 v128, v128
	v_rcp_f32_e32 v129, v129
	v_rcp_f32_e32 v180, v180
	v_rcp_f32_e32 v181, v181
	v_mul_f32_e32 v128, v128, v178
	v_mul_f32_e32 v129, v129, v171
	v_mul_f32_e32 v180, v180, v179
	v_mul_f32_e32 v181, v181, v175
	v_mul_f32_e32 v128, v128, v180
	v_mul_f32_e32 v129, v129, v181
	v_lshlrev_b32_e32 v178, 16, v172
	v_and_b32_e32 v172, 0xffff0000, v172
	v_lshlrev_b32_e32 v179, 16, v176
	v_and_b32_e32 v176, 0xffff0000, v176
	v_mul_f32_e32 v122, 0xbfb8aa3b, v122
	v_mul_f32_e32 v123, 0xbfb8aa3b, v123
	v_mul_f32_e32 v180, 0xbfb8aa3b, v179
	v_mul_f32_e32 v181, 0xbfb8aa3b, v176
	v_exp_f32_e32 v122, v122
	v_exp_f32_e32 v123, v123
	v_exp_f32_e32 v180, v180
	v_exp_f32_e32 v181, v181
	v_add_f32_e32 v122, 1.0, v122
	v_add_f32_e32 v123, 1.0, v123
	v_add_f32_e32 v180, 1.0, v180
	v_add_f32_e32 v181, 1.0, v181
	v_rcp_f32_e32 v122, v122
	v_rcp_f32_e32 v123, v123
	v_rcp_f32_e32 v180, v180
	v_rcp_f32_e32 v181, v181
	v_mul_f32_e32 v122, v122, v178
	v_mul_f32_e32 v123, v123, v172
	v_mul_f32_e32 v180, v180, v179
	v_mul_f32_e32 v181, v181, v176
	v_mul_f32_e32 v122, v122, v180
	v_mul_f32_e32 v123, v123, v181
	v_lshlrev_b32_e32 v178, 16, v173
	v_and_b32_e32 v173, 0xffff0000, v173
	v_lshlrev_b32_e32 v179, 16, v177
	v_and_b32_e32 v177, 0xffff0000, v177
	v_mul_f32_e32 v124, 0xbfb8aa3b, v124
	v_mul_f32_e32 v125, 0xbfb8aa3b, v125
	v_mul_f32_e32 v180, 0xbfb8aa3b, v179
	v_mul_f32_e32 v181, 0xbfb8aa3b, v177
	v_exp_f32_e32 v124, v124
	v_exp_f32_e32 v125, v125
	v_exp_f32_e32 v180, v180
	v_exp_f32_e32 v181, v181
	v_add_f32_e32 v124, 1.0, v124
	v_add_f32_e32 v125, 1.0, v125
	v_add_f32_e32 v180, 1.0, v180
	v_add_f32_e32 v181, 1.0, v181
	v_rcp_f32_e32 v124, v124
	v_rcp_f32_e32 v125, v125
	v_rcp_f32_e32 v180, v180
	v_rcp_f32_e32 v181, v181
	v_mul_f32_e32 v124, v124, v178
	v_mul_f32_e32 v125, v125, v173
	v_mul_f32_e32 v180, v180, v179
	v_mul_f32_e32 v181, v181, v177
	v_mul_f32_e32 v124, v124, v180
	v_mul_f32_e32 v125, v125, v181
	v_cvt_pk_bf16_f32 v126, v126, v127
	v_cvt_pk_bf16_f32 v127, v128, v129
	v_cvt_pk_bf16_f32 v128, v122, v123
	v_cvt_pk_bf16_f32 v129, v124, v125
	global_store_dwordx4 v[146:147], v[126:129], off
	global_load_dwordx4 v[170:173], v[142:143], off offset:256
	global_load_dwordx4 v[174:177], v[144:145], off offset:256
	s_waitcnt vmcnt(5)
	v_lshlrev_b32_e32 v178, 16, v154
	v_and_b32_e32 v154, 0xffff0000, v154
	v_lshlrev_b32_e32 v179, 16, v158
	v_and_b32_e32 v158, 0xffff0000, v158
	v_mul_f32_e32 v118, 0xbfb8aa3b, v118
	v_mul_f32_e32 v119, 0xbfb8aa3b, v119
	v_mul_f32_e32 v180, 0xbfb8aa3b, v179
	v_mul_f32_e32 v181, 0xbfb8aa3b, v158
	v_exp_f32_e32 v118, v118
	v_exp_f32_e32 v119, v119
	v_exp_f32_e32 v180, v180
	v_exp_f32_e32 v181, v181
	v_add_f32_e32 v118, 1.0, v118
	v_add_f32_e32 v119, 1.0, v119
	v_add_f32_e32 v180, 1.0, v180
	v_add_f32_e32 v181, 1.0, v181
	v_rcp_f32_e32 v118, v118
	v_rcp_f32_e32 v119, v119
	v_rcp_f32_e32 v180, v180
	v_rcp_f32_e32 v181, v181
	v_mul_f32_e32 v118, v118, v178
	v_mul_f32_e32 v119, v119, v154
	v_mul_f32_e32 v180, v180, v179
	v_mul_f32_e32 v181, v181, v158
	v_mul_f32_e32 v118, v118, v180
	v_mul_f32_e32 v119, v119, v181
	v_lshlrev_b32_e32 v178, 16, v155
	v_and_b32_e32 v155, 0xffff0000, v155
	v_lshlrev_b32_e32 v179, 16, v159
	v_and_b32_e32 v159, 0xffff0000, v159
	v_mul_f32_e32 v120, 0xbfb8aa3b, v120
	v_mul_f32_e32 v121, 0xbfb8aa3b, v121
	v_mul_f32_e32 v180, 0xbfb8aa3b, v179
	v_mul_f32_e32 v181, 0xbfb8aa3b, v159
	v_exp_f32_e32 v120, v120
	v_exp_f32_e32 v121, v121
	v_exp_f32_e32 v180, v180
	v_exp_f32_e32 v181, v181
	v_add_f32_e32 v120, 1.0, v120
	v_add_f32_e32 v121, 1.0, v121
	v_add_f32_e32 v180, 1.0, v180
	v_add_f32_e32 v181, 1.0, v181
	v_rcp_f32_e32 v120, v120
	v_rcp_f32_e32 v121, v121
	v_rcp_f32_e32 v180, v180
	v_rcp_f32_e32 v181, v181
	v_mul_f32_e32 v120, v120, v178
	v_mul_f32_e32 v121, v121, v155
	v_mul_f32_e32 v180, v180, v179
	v_mul_f32_e32 v181, v181, v159
	v_mul_f32_e32 v120, v120, v180
	v_mul_f32_e32 v121, v121, v181
	v_lshlrev_b32_e32 v178, 16, v156
	v_and_b32_e32 v156, 0xffff0000, v156
	v_lshlrev_b32_e32 v179, 16, v160
	v_and_b32_e32 v160, 0xffff0000, v160
	v_mul_f32_e32 v114, 0xbfb8aa3b, v114
	v_mul_f32_e32 v115, 0xbfb8aa3b, v115
	v_mul_f32_e32 v180, 0xbfb8aa3b, v179
	v_mul_f32_e32 v181, 0xbfb8aa3b, v160
	v_exp_f32_e32 v114, v114
	v_exp_f32_e32 v115, v115
	v_exp_f32_e32 v180, v180
	v_exp_f32_e32 v181, v181
	v_add_f32_e32 v114, 1.0, v114
	v_add_f32_e32 v115, 1.0, v115
	v_add_f32_e32 v180, 1.0, v180
	v_add_f32_e32 v181, 1.0, v181
	v_rcp_f32_e32 v114, v114
	v_rcp_f32_e32 v115, v115
	v_rcp_f32_e32 v180, v180
	v_rcp_f32_e32 v181, v181
	v_mul_f32_e32 v114, v114, v178
	v_mul_f32_e32 v115, v115, v156
	v_mul_f32_e32 v180, v180, v179
	v_mul_f32_e32 v181, v181, v160
	v_mul_f32_e32 v114, v114, v180
	v_mul_f32_e32 v115, v115, v181
	v_lshlrev_b32_e32 v178, 16, v157
	v_and_b32_e32 v157, 0xffff0000, v157
	v_lshlrev_b32_e32 v179, 16, v161
	v_and_b32_e32 v161, 0xffff0000, v161
	v_mul_f32_e32 v116, 0xbfb8aa3b, v116
	v_mul_f32_e32 v117, 0xbfb8aa3b, v117
	v_mul_f32_e32 v180, 0xbfb8aa3b, v179
	v_mul_f32_e32 v181, 0xbfb8aa3b, v161
	v_exp_f32_e32 v116, v116
	v_exp_f32_e32 v117, v117
	v_exp_f32_e32 v180, v180
	v_exp_f32_e32 v181, v181
	v_add_f32_e32 v116, 1.0, v116
	v_add_f32_e32 v117, 1.0, v117
	v_add_f32_e32 v180, 1.0, v180
	v_add_f32_e32 v181, 1.0, v181
	v_rcp_f32_e32 v116, v116
	v_rcp_f32_e32 v117, v117
	v_rcp_f32_e32 v180, v180
	v_rcp_f32_e32 v181, v181
	v_mul_f32_e32 v116, v116, v178
	v_mul_f32_e32 v117, v117, v157
	v_mul_f32_e32 v180, v180, v179
	v_mul_f32_e32 v181, v181, v161
	v_mul_f32_e32 v116, v116, v180
	v_mul_f32_e32 v117, v117, v181
	v_cvt_pk_bf16_f32 v118, v118, v119
	v_cvt_pk_bf16_f32 v119, v120, v121
	v_cvt_pk_bf16_f32 v120, v114, v115
	v_cvt_pk_bf16_f32 v121, v116, v117
	global_store_dwordx4 v[146:147], v[118:121], off offset:256
	s_mov_b64 s[58:59], 0x20000
	v_lshl_add_u64 v[146:147], v[146:147], 0, s[58:59]
	s_mov_b64 s[58:59], 0x8000
	v_lshl_add_u64 v[142:143], v[142:143], 0, s[58:59]
	s_mov_b64 s[58:59], 0x4000
	v_lshl_add_u64 v[144:145], v[144:145], 0, s[58:59]
	global_load_dwordx4 v[154:157], v[142:143], off
	global_load_dwordx4 v[158:161], v[144:145], off
	s_waitcnt vmcnt(6)
	v_lshlrev_b32_e32 v178, 16, v162
	v_and_b32_e32 v162, 0xffff0000, v162
	v_lshlrev_b32_e32 v179, 16, v166
	v_and_b32_e32 v166, 0xffff0000, v166
	v_mul_f32_e32 v110, 0xbfb8aa3b, v110
	v_mul_f32_e32 v111, 0xbfb8aa3b, v111
	v_mul_f32_e32 v180, 0xbfb8aa3b, v179
	v_mul_f32_e32 v181, 0xbfb8aa3b, v166
	v_exp_f32_e32 v110, v110
	v_exp_f32_e32 v111, v111
	v_exp_f32_e32 v180, v180
	v_exp_f32_e32 v181, v181
	v_add_f32_e32 v110, 1.0, v110
	v_add_f32_e32 v111, 1.0, v111
	v_add_f32_e32 v180, 1.0, v180
	v_add_f32_e32 v181, 1.0, v181
	v_rcp_f32_e32 v110, v110
	v_rcp_f32_e32 v111, v111
	v_rcp_f32_e32 v180, v180
	v_rcp_f32_e32 v181, v181
	v_mul_f32_e32 v110, v110, v178
	v_mul_f32_e32 v111, v111, v162
	v_mul_f32_e32 v180, v180, v179
	v_mul_f32_e32 v181, v181, v166
	v_mul_f32_e32 v110, v110, v180
	v_mul_f32_e32 v111, v111, v181
	v_lshlrev_b32_e32 v178, 16, v163
	v_and_b32_e32 v163, 0xffff0000, v163
	v_lshlrev_b32_e32 v179, 16, v167
	v_and_b32_e32 v167, 0xffff0000, v167
	v_mul_f32_e32 v112, 0xbfb8aa3b, v112
	v_mul_f32_e32 v113, 0xbfb8aa3b, v113
	v_mul_f32_e32 v180, 0xbfb8aa3b, v179
	v_mul_f32_e32 v181, 0xbfb8aa3b, v167
	v_exp_f32_e32 v112, v112
	v_exp_f32_e32 v113, v113
	v_exp_f32_e32 v180, v180
	v_exp_f32_e32 v181, v181
	v_add_f32_e32 v112, 1.0, v112
	v_add_f32_e32 v113, 1.0, v113
	v_add_f32_e32 v180, 1.0, v180
	v_add_f32_e32 v181, 1.0, v181
	v_rcp_f32_e32 v112, v112
	v_rcp_f32_e32 v113, v113
	v_rcp_f32_e32 v180, v180
	v_rcp_f32_e32 v181, v181
	v_mul_f32_e32 v112, v112, v178
	v_mul_f32_e32 v113, v113, v163
	v_mul_f32_e32 v180, v180, v179
	v_mul_f32_e32 v181, v181, v167
	v_mul_f32_e32 v112, v112, v180
	v_mul_f32_e32 v113, v113, v181
	v_lshlrev_b32_e32 v178, 16, v164
	v_and_b32_e32 v164, 0xffff0000, v164
	v_lshlrev_b32_e32 v179, 16, v168
	v_and_b32_e32 v168, 0xffff0000, v168
	v_mul_f32_e32 v106, 0xbfb8aa3b, v106
	v_mul_f32_e32 v107, 0xbfb8aa3b, v107
	v_mul_f32_e32 v180, 0xbfb8aa3b, v179
	v_mul_f32_e32 v181, 0xbfb8aa3b, v168
	v_exp_f32_e32 v106, v106
	v_exp_f32_e32 v107, v107
	v_exp_f32_e32 v180, v180
	v_exp_f32_e32 v181, v181
	v_add_f32_e32 v106, 1.0, v106
	v_add_f32_e32 v107, 1.0, v107
	v_add_f32_e32 v180, 1.0, v180
	v_add_f32_e32 v181, 1.0, v181
	v_rcp_f32_e32 v106, v106
	v_rcp_f32_e32 v107, v107
	v_rcp_f32_e32 v180, v180
	v_rcp_f32_e32 v181, v181
	v_mul_f32_e32 v106, v106, v178
	v_mul_f32_e32 v107, v107, v164
	v_mul_f32_e32 v180, v180, v179
	v_mul_f32_e32 v181, v181, v168
	v_mul_f32_e32 v106, v106, v180
	v_mul_f32_e32 v107, v107, v181
	v_lshlrev_b32_e32 v178, 16, v165
	v_and_b32_e32 v165, 0xffff0000, v165
	v_lshlrev_b32_e32 v179, 16, v169
	v_and_b32_e32 v169, 0xffff0000, v169
	v_mul_f32_e32 v108, 0xbfb8aa3b, v108
	v_mul_f32_e32 v109, 0xbfb8aa3b, v109
	v_mul_f32_e32 v180, 0xbfb8aa3b, v179
	v_mul_f32_e32 v181, 0xbfb8aa3b, v169
	v_exp_f32_e32 v108, v108
	v_exp_f32_e32 v109, v109
	v_exp_f32_e32 v180, v180
	v_exp_f32_e32 v181, v181
	v_add_f32_e32 v108, 1.0, v108
	v_add_f32_e32 v109, 1.0, v109
	v_add_f32_e32 v180, 1.0, v180
	v_add_f32_e32 v181, 1.0, v181
	v_rcp_f32_e32 v108, v108
	v_rcp_f32_e32 v109, v109
	v_rcp_f32_e32 v180, v180
	v_rcp_f32_e32 v181, v181
	v_mul_f32_e32 v108, v108, v178
	v_mul_f32_e32 v109, v109, v165
	v_mul_f32_e32 v180, v180, v179
	v_mul_f32_e32 v181, v181, v169
	v_mul_f32_e32 v108, v108, v180
	v_mul_f32_e32 v109, v109, v181
	v_cvt_pk_bf16_f32 v110, v110, v111
	v_cvt_pk_bf16_f32 v111, v112, v113
	v_cvt_pk_bf16_f32 v112, v106, v107
	v_cvt_pk_bf16_f32 v113, v108, v109
	global_store_dwordx4 v[146:147], v[110:113], off
	global_load_dwordx4 v[162:165], v[142:143], off offset:256
	global_load_dwordx4 v[166:169], v[144:145], off offset:256
	s_waitcnt vmcnt(6)
	v_lshlrev_b32_e32 v178, 16, v170
	v_and_b32_e32 v170, 0xffff0000, v170
	v_lshlrev_b32_e32 v179, 16, v174
	v_and_b32_e32 v174, 0xffff0000, v174
	v_mul_f32_e32 v102, 0xbfb8aa3b, v102
	v_mul_f32_e32 v103, 0xbfb8aa3b, v103
	v_mul_f32_e32 v180, 0xbfb8aa3b, v179
	v_mul_f32_e32 v181, 0xbfb8aa3b, v174
	v_exp_f32_e32 v102, v102
	v_exp_f32_e32 v103, v103
	v_exp_f32_e32 v180, v180
	v_exp_f32_e32 v181, v181
	v_add_f32_e32 v102, 1.0, v102
	v_add_f32_e32 v103, 1.0, v103
	v_add_f32_e32 v180, 1.0, v180
	v_add_f32_e32 v181, 1.0, v181
	v_rcp_f32_e32 v102, v102
	v_rcp_f32_e32 v103, v103
	v_rcp_f32_e32 v180, v180
	v_rcp_f32_e32 v181, v181
	v_mul_f32_e32 v102, v102, v178
	v_mul_f32_e32 v103, v103, v170
	v_mul_f32_e32 v180, v180, v179
	v_mul_f32_e32 v181, v181, v174
	v_mul_f32_e32 v102, v102, v180
	v_mul_f32_e32 v103, v103, v181
	v_lshlrev_b32_e32 v178, 16, v171
	v_and_b32_e32 v171, 0xffff0000, v171
	v_lshlrev_b32_e32 v179, 16, v175
	v_and_b32_e32 v175, 0xffff0000, v175
	v_mul_f32_e32 v104, 0xbfb8aa3b, v104
	v_mul_f32_e32 v105, 0xbfb8aa3b, v105
	v_mul_f32_e32 v180, 0xbfb8aa3b, v179
	v_mul_f32_e32 v181, 0xbfb8aa3b, v175
	v_exp_f32_e32 v104, v104
	v_exp_f32_e32 v105, v105
	v_exp_f32_e32 v180, v180
	v_exp_f32_e32 v181, v181
	v_add_f32_e32 v104, 1.0, v104
	v_add_f32_e32 v105, 1.0, v105
	v_add_f32_e32 v180, 1.0, v180
	v_add_f32_e32 v181, 1.0, v181
	v_rcp_f32_e32 v104, v104
	v_rcp_f32_e32 v105, v105
	v_rcp_f32_e32 v180, v180
	v_rcp_f32_e32 v181, v181
	v_mul_f32_e32 v104, v104, v178
	v_mul_f32_e32 v105, v105, v171
	v_mul_f32_e32 v180, v180, v179
	v_mul_f32_e32 v181, v181, v175
	v_mul_f32_e32 v104, v104, v180
	v_mul_f32_e32 v105, v105, v181
	v_lshlrev_b32_e32 v178, 16, v172
	v_and_b32_e32 v172, 0xffff0000, v172
	v_lshlrev_b32_e32 v179, 16, v176
	v_and_b32_e32 v176, 0xffff0000, v176
	v_mul_f32_e32 v98, 0xbfb8aa3b, v98
	v_mul_f32_e32 v99, 0xbfb8aa3b, v99
	v_mul_f32_e32 v180, 0xbfb8aa3b, v179
	v_mul_f32_e32 v181, 0xbfb8aa3b, v176
	v_exp_f32_e32 v98, v98
	v_exp_f32_e32 v99, v99
	v_exp_f32_e32 v180, v180
	v_exp_f32_e32 v181, v181
	v_add_f32_e32 v98, 1.0, v98
	v_add_f32_e32 v99, 1.0, v99
	v_add_f32_e32 v180, 1.0, v180
	v_add_f32_e32 v181, 1.0, v181
	v_rcp_f32_e32 v98, v98
	v_rcp_f32_e32 v99, v99
	v_rcp_f32_e32 v180, v180
	v_rcp_f32_e32 v181, v181
	v_mul_f32_e32 v98, v98, v178
	v_mul_f32_e32 v99, v99, v172
	v_mul_f32_e32 v180, v180, v179
	v_mul_f32_e32 v181, v181, v176
	v_mul_f32_e32 v98, v98, v180
	v_mul_f32_e32 v99, v99, v181
	v_lshlrev_b32_e32 v178, 16, v173
	v_and_b32_e32 v173, 0xffff0000, v173
	v_lshlrev_b32_e32 v179, 16, v177
	v_and_b32_e32 v177, 0xffff0000, v177
	v_mul_f32_e32 v100, 0xbfb8aa3b, v100
	v_mul_f32_e32 v101, 0xbfb8aa3b, v101
	v_mul_f32_e32 v180, 0xbfb8aa3b, v179
	v_mul_f32_e32 v181, 0xbfb8aa3b, v177
	v_exp_f32_e32 v100, v100
	v_exp_f32_e32 v101, v101
	v_exp_f32_e32 v180, v180
	v_exp_f32_e32 v181, v181
	v_add_f32_e32 v100, 1.0, v100
	v_add_f32_e32 v101, 1.0, v101
	v_add_f32_e32 v180, 1.0, v180
	v_add_f32_e32 v181, 1.0, v181
	v_rcp_f32_e32 v100, v100
	v_rcp_f32_e32 v101, v101
	v_rcp_f32_e32 v180, v180
	v_rcp_f32_e32 v181, v181
	v_mul_f32_e32 v100, v100, v178
	v_mul_f32_e32 v101, v101, v173
	v_mul_f32_e32 v180, v180, v179
	v_mul_f32_e32 v181, v181, v177
	v_mul_f32_e32 v100, v100, v180
	v_mul_f32_e32 v101, v101, v181
	v_cvt_pk_bf16_f32 v102, v102, v103
	v_cvt_pk_bf16_f32 v103, v104, v105
	v_cvt_pk_bf16_f32 v104, v98, v99
	v_cvt_pk_bf16_f32 v105, v100, v101
	global_store_dwordx4 v[146:147], v[102:105], off offset:256
	s_mov_b64 s[58:59], 0x20000
	v_lshl_add_u64 v[146:147], v[146:147], 0, s[58:59]
	s_mov_b64 s[58:59], 0x8000
	v_lshl_add_u64 v[142:143], v[142:143], 0, s[58:59]
	s_mov_b64 s[58:59], 0x4000
	v_lshl_add_u64 v[144:145], v[144:145], 0, s[58:59]
	global_load_dwordx4 v[170:173], v[142:143], off
	global_load_dwordx4 v[174:177], v[144:145], off
	s_waitcnt vmcnt(6)
	v_lshlrev_b32_e32 v178, 16, v154
	v_and_b32_e32 v154, 0xffff0000, v154
	v_lshlrev_b32_e32 v179, 16, v158
	v_and_b32_e32 v158, 0xffff0000, v158
	v_mul_f32_e32 v94, 0xbfb8aa3b, v94
	v_mul_f32_e32 v95, 0xbfb8aa3b, v95
	v_mul_f32_e32 v180, 0xbfb8aa3b, v179
	v_mul_f32_e32 v181, 0xbfb8aa3b, v158
	v_exp_f32_e32 v94, v94
	v_exp_f32_e32 v95, v95
	v_exp_f32_e32 v180, v180
	v_exp_f32_e32 v181, v181
	v_add_f32_e32 v94, 1.0, v94
	v_add_f32_e32 v95, 1.0, v95
	v_add_f32_e32 v180, 1.0, v180
	v_add_f32_e32 v181, 1.0, v181
	v_rcp_f32_e32 v94, v94
	v_rcp_f32_e32 v95, v95
	v_rcp_f32_e32 v180, v180
	v_rcp_f32_e32 v181, v181
	v_mul_f32_e32 v94, v94, v178
	v_mul_f32_e32 v95, v95, v154
	v_mul_f32_e32 v180, v180, v179
	v_mul_f32_e32 v181, v181, v158
	v_mul_f32_e32 v94, v94, v180
	v_mul_f32_e32 v95, v95, v181
	v_lshlrev_b32_e32 v178, 16, v155
	v_and_b32_e32 v155, 0xffff0000, v155
	v_lshlrev_b32_e32 v179, 16, v159
	v_and_b32_e32 v159, 0xffff0000, v159
	v_mul_f32_e32 v96, 0xbfb8aa3b, v96
	v_mul_f32_e32 v97, 0xbfb8aa3b, v97
	v_mul_f32_e32 v180, 0xbfb8aa3b, v179
	v_mul_f32_e32 v181, 0xbfb8aa3b, v159
	v_exp_f32_e32 v96, v96
	v_exp_f32_e32 v97, v97
	v_exp_f32_e32 v180, v180
	v_exp_f32_e32 v181, v181
	v_add_f32_e32 v96, 1.0, v96
	v_add_f32_e32 v97, 1.0, v97
	v_add_f32_e32 v180, 1.0, v180
	v_add_f32_e32 v181, 1.0, v181
	v_rcp_f32_e32 v96, v96
	v_rcp_f32_e32 v97, v97
	v_rcp_f32_e32 v180, v180
	v_rcp_f32_e32 v181, v181
	v_mul_f32_e32 v96, v96, v178
	v_mul_f32_e32 v97, v97, v155
	v_mul_f32_e32 v180, v180, v179
	v_mul_f32_e32 v181, v181, v159
	v_mul_f32_e32 v96, v96, v180
	v_mul_f32_e32 v97, v97, v181
	v_lshlrev_b32_e32 v178, 16, v156
	v_and_b32_e32 v156, 0xffff0000, v156
	v_lshlrev_b32_e32 v179, 16, v160
	v_and_b32_e32 v160, 0xffff0000, v160
	v_mul_f32_e32 v90, 0xbfb8aa3b, v90
	v_mul_f32_e32 v91, 0xbfb8aa3b, v91
	v_mul_f32_e32 v180, 0xbfb8aa3b, v179
	v_mul_f32_e32 v181, 0xbfb8aa3b, v160
	v_exp_f32_e32 v90, v90
	v_exp_f32_e32 v91, v91
	v_exp_f32_e32 v180, v180
	v_exp_f32_e32 v181, v181
	v_add_f32_e32 v90, 1.0, v90
	v_add_f32_e32 v91, 1.0, v91
	v_add_f32_e32 v180, 1.0, v180
	v_add_f32_e32 v181, 1.0, v181
	v_rcp_f32_e32 v90, v90
	v_rcp_f32_e32 v91, v91
	v_rcp_f32_e32 v180, v180
	v_rcp_f32_e32 v181, v181
	v_mul_f32_e32 v90, v90, v178
	v_mul_f32_e32 v91, v91, v156
	v_mul_f32_e32 v180, v180, v179
	v_mul_f32_e32 v181, v181, v160
	v_mul_f32_e32 v90, v90, v180
	v_mul_f32_e32 v91, v91, v181
	v_lshlrev_b32_e32 v178, 16, v157
	v_and_b32_e32 v157, 0xffff0000, v157
	v_lshlrev_b32_e32 v179, 16, v161
	v_and_b32_e32 v161, 0xffff0000, v161
	v_mul_f32_e32 v92, 0xbfb8aa3b, v92
	v_mul_f32_e32 v93, 0xbfb8aa3b, v93
	v_mul_f32_e32 v180, 0xbfb8aa3b, v179
	v_mul_f32_e32 v181, 0xbfb8aa3b, v161
	v_exp_f32_e32 v92, v92
	v_exp_f32_e32 v93, v93
	v_exp_f32_e32 v180, v180
	v_exp_f32_e32 v181, v181
	v_add_f32_e32 v92, 1.0, v92
	v_add_f32_e32 v93, 1.0, v93
	v_add_f32_e32 v180, 1.0, v180
	v_add_f32_e32 v181, 1.0, v181
	v_rcp_f32_e32 v92, v92
	v_rcp_f32_e32 v93, v93
	v_rcp_f32_e32 v180, v180
	v_rcp_f32_e32 v181, v181
	v_mul_f32_e32 v92, v92, v178
	v_mul_f32_e32 v93, v93, v157
	v_mul_f32_e32 v180, v180, v179
	v_mul_f32_e32 v181, v181, v161
	v_mul_f32_e32 v92, v92, v180
	v_mul_f32_e32 v93, v93, v181
	v_cvt_pk_bf16_f32 v94, v94, v95
	v_cvt_pk_bf16_f32 v95, v96, v97
	v_cvt_pk_bf16_f32 v96, v90, v91
	v_cvt_pk_bf16_f32 v97, v92, v93
	global_store_dwordx4 v[146:147], v[94:97], off
	global_load_dwordx4 v[154:157], v[142:143], off offset:256
	global_load_dwordx4 v[158:161], v[144:145], off offset:256
	s_waitcnt vmcnt(6)
	v_lshlrev_b32_e32 v178, 16, v162
	v_and_b32_e32 v162, 0xffff0000, v162
	v_lshlrev_b32_e32 v179, 16, v166
	v_and_b32_e32 v166, 0xffff0000, v166
	v_mul_f32_e32 v86, 0xbfb8aa3b, v86
	v_mul_f32_e32 v87, 0xbfb8aa3b, v87
	v_mul_f32_e32 v180, 0xbfb8aa3b, v179
	v_mul_f32_e32 v181, 0xbfb8aa3b, v166
	v_exp_f32_e32 v86, v86
	v_exp_f32_e32 v87, v87
	v_exp_f32_e32 v180, v180
	v_exp_f32_e32 v181, v181
	v_add_f32_e32 v86, 1.0, v86
	v_add_f32_e32 v87, 1.0, v87
	v_add_f32_e32 v180, 1.0, v180
	v_add_f32_e32 v181, 1.0, v181
	v_rcp_f32_e32 v86, v86
	v_rcp_f32_e32 v87, v87
	v_rcp_f32_e32 v180, v180
	v_rcp_f32_e32 v181, v181
	v_mul_f32_e32 v86, v86, v178
	v_mul_f32_e32 v87, v87, v162
	v_mul_f32_e32 v180, v180, v179
	v_mul_f32_e32 v181, v181, v166
	v_mul_f32_e32 v86, v86, v180
	v_mul_f32_e32 v87, v87, v181
	v_lshlrev_b32_e32 v178, 16, v163
	v_and_b32_e32 v163, 0xffff0000, v163
	v_lshlrev_b32_e32 v179, 16, v167
	v_and_b32_e32 v167, 0xffff0000, v167
	v_mul_f32_e32 v88, 0xbfb8aa3b, v88
	v_mul_f32_e32 v89, 0xbfb8aa3b, v89
	v_mul_f32_e32 v180, 0xbfb8aa3b, v179
	v_mul_f32_e32 v181, 0xbfb8aa3b, v167
	v_exp_f32_e32 v88, v88
	v_exp_f32_e32 v89, v89
	v_exp_f32_e32 v180, v180
	v_exp_f32_e32 v181, v181
	v_add_f32_e32 v88, 1.0, v88
	v_add_f32_e32 v89, 1.0, v89
	v_add_f32_e32 v180, 1.0, v180
	v_add_f32_e32 v181, 1.0, v181
	v_rcp_f32_e32 v88, v88
	v_rcp_f32_e32 v89, v89
	v_rcp_f32_e32 v180, v180
	v_rcp_f32_e32 v181, v181
	v_mul_f32_e32 v88, v88, v178
	v_mul_f32_e32 v89, v89, v163
	v_mul_f32_e32 v180, v180, v179
	v_mul_f32_e32 v181, v181, v167
	v_mul_f32_e32 v88, v88, v180
	v_mul_f32_e32 v89, v89, v181
	v_lshlrev_b32_e32 v178, 16, v164
	v_and_b32_e32 v164, 0xffff0000, v164
	v_lshlrev_b32_e32 v179, 16, v168
	v_and_b32_e32 v168, 0xffff0000, v168
	v_mul_f32_e32 v82, 0xbfb8aa3b, v82
	v_mul_f32_e32 v83, 0xbfb8aa3b, v83
	v_mul_f32_e32 v180, 0xbfb8aa3b, v179
	v_mul_f32_e32 v181, 0xbfb8aa3b, v168
	v_exp_f32_e32 v82, v82
	v_exp_f32_e32 v83, v83
	v_exp_f32_e32 v180, v180
	v_exp_f32_e32 v181, v181
	v_add_f32_e32 v82, 1.0, v82
	v_add_f32_e32 v83, 1.0, v83
	v_add_f32_e32 v180, 1.0, v180
	v_add_f32_e32 v181, 1.0, v181
	v_rcp_f32_e32 v82, v82
	v_rcp_f32_e32 v83, v83
	v_rcp_f32_e32 v180, v180
	v_rcp_f32_e32 v181, v181
	v_mul_f32_e32 v82, v82, v178
	v_mul_f32_e32 v83, v83, v164
	v_mul_f32_e32 v180, v180, v179
	v_mul_f32_e32 v181, v181, v168
	v_mul_f32_e32 v82, v82, v180
	v_mul_f32_e32 v83, v83, v181
	v_lshlrev_b32_e32 v178, 16, v165
	v_and_b32_e32 v165, 0xffff0000, v165
	v_lshlrev_b32_e32 v179, 16, v169
	v_and_b32_e32 v169, 0xffff0000, v169
	v_mul_f32_e32 v84, 0xbfb8aa3b, v84
	v_mul_f32_e32 v85, 0xbfb8aa3b, v85
	v_mul_f32_e32 v180, 0xbfb8aa3b, v179
	v_mul_f32_e32 v181, 0xbfb8aa3b, v169
	v_exp_f32_e32 v84, v84
	v_exp_f32_e32 v85, v85
	v_exp_f32_e32 v180, v180
	v_exp_f32_e32 v181, v181
	v_add_f32_e32 v84, 1.0, v84
	v_add_f32_e32 v85, 1.0, v85
	v_add_f32_e32 v180, 1.0, v180
	v_add_f32_e32 v181, 1.0, v181
	v_rcp_f32_e32 v84, v84
	v_rcp_f32_e32 v85, v85
	v_rcp_f32_e32 v180, v180
	v_rcp_f32_e32 v181, v181
	v_mul_f32_e32 v84, v84, v178
	v_mul_f32_e32 v85, v85, v165
	v_mul_f32_e32 v180, v180, v179
	v_mul_f32_e32 v181, v181, v169
	v_mul_f32_e32 v84, v84, v180
	v_mul_f32_e32 v85, v85, v181
	v_cvt_pk_bf16_f32 v86, v86, v87
	v_cvt_pk_bf16_f32 v87, v88, v89
	v_cvt_pk_bf16_f32 v88, v82, v83
	v_cvt_pk_bf16_f32 v89, v84, v85
	global_store_dwordx4 v[146:147], v[86:89], off offset:256
	s_mov_b64 s[58:59], 0x20000
	v_lshl_add_u64 v[146:147], v[146:147], 0, s[58:59]
	s_mov_b64 s[58:59], 0x28000
	v_lshl_add_u64 v[142:143], v[142:143], 0, s[58:59]
	s_mov_b64 s[58:59], 0x14000
	v_lshl_add_u64 v[144:145], v[144:145], 0, s[58:59]
	global_load_dwordx4 v[162:165], v[142:143], off
	global_load_dwordx4 v[166:169], v[144:145], off
	s_waitcnt vmcnt(6)
	v_lshlrev_b32_e32 v178, 16, v170
	v_and_b32_e32 v170, 0xffff0000, v170
	v_lshlrev_b32_e32 v179, 16, v174
	v_and_b32_e32 v174, 0xffff0000, v174
	v_mul_f32_e32 v78, 0xbfb8aa3b, v78
	v_mul_f32_e32 v79, 0xbfb8aa3b, v79
	v_mul_f32_e32 v180, 0xbfb8aa3b, v179
	v_mul_f32_e32 v181, 0xbfb8aa3b, v174
	v_exp_f32_e32 v78, v78
	v_exp_f32_e32 v79, v79
	v_exp_f32_e32 v180, v180
	v_exp_f32_e32 v181, v181
	v_add_f32_e32 v78, 1.0, v78
	v_add_f32_e32 v79, 1.0, v79
	v_add_f32_e32 v180, 1.0, v180
	v_add_f32_e32 v181, 1.0, v181
	v_rcp_f32_e32 v78, v78
	v_rcp_f32_e32 v79, v79
	v_rcp_f32_e32 v180, v180
	v_rcp_f32_e32 v181, v181
	v_mul_f32_e32 v78, v78, v178
	v_mul_f32_e32 v79, v79, v170
	v_mul_f32_e32 v180, v180, v179
	v_mul_f32_e32 v181, v181, v174
	v_mul_f32_e32 v78, v78, v180
	v_mul_f32_e32 v79, v79, v181
	v_lshlrev_b32_e32 v178, 16, v171
	v_and_b32_e32 v171, 0xffff0000, v171
	v_lshlrev_b32_e32 v179, 16, v175
	v_and_b32_e32 v175, 0xffff0000, v175
	v_mul_f32_e32 v80, 0xbfb8aa3b, v80
	v_mul_f32_e32 v81, 0xbfb8aa3b, v81
	v_mul_f32_e32 v180, 0xbfb8aa3b, v179
	v_mul_f32_e32 v181, 0xbfb8aa3b, v175
	v_exp_f32_e32 v80, v80
	v_exp_f32_e32 v81, v81
	v_exp_f32_e32 v180, v180
	v_exp_f32_e32 v181, v181
	v_add_f32_e32 v80, 1.0, v80
	v_add_f32_e32 v81, 1.0, v81
	v_add_f32_e32 v180, 1.0, v180
	v_add_f32_e32 v181, 1.0, v181
	v_rcp_f32_e32 v80, v80
	v_rcp_f32_e32 v81, v81
	v_rcp_f32_e32 v180, v180
	v_rcp_f32_e32 v181, v181
	v_mul_f32_e32 v80, v80, v178
	v_mul_f32_e32 v81, v81, v171
	v_mul_f32_e32 v180, v180, v179
	v_mul_f32_e32 v181, v181, v175
	v_mul_f32_e32 v80, v80, v180
	v_mul_f32_e32 v81, v81, v181
	v_lshlrev_b32_e32 v178, 16, v172
	v_and_b32_e32 v172, 0xffff0000, v172
	v_lshlrev_b32_e32 v179, 16, v176
	v_and_b32_e32 v176, 0xffff0000, v176
	v_mul_f32_e32 v74, 0xbfb8aa3b, v74
	v_mul_f32_e32 v75, 0xbfb8aa3b, v75
	v_mul_f32_e32 v180, 0xbfb8aa3b, v179
	v_mul_f32_e32 v181, 0xbfb8aa3b, v176
	v_exp_f32_e32 v74, v74
	v_exp_f32_e32 v75, v75
	v_exp_f32_e32 v180, v180
	v_exp_f32_e32 v181, v181
	v_add_f32_e32 v74, 1.0, v74
	v_add_f32_e32 v75, 1.0, v75
	v_add_f32_e32 v180, 1.0, v180
	v_add_f32_e32 v181, 1.0, v181
	v_rcp_f32_e32 v74, v74
	v_rcp_f32_e32 v75, v75
	v_rcp_f32_e32 v180, v180
	v_rcp_f32_e32 v181, v181
	v_mul_f32_e32 v74, v74, v178
	v_mul_f32_e32 v75, v75, v172
	v_mul_f32_e32 v180, v180, v179
	v_mul_f32_e32 v181, v181, v176
	v_mul_f32_e32 v74, v74, v180
	v_mul_f32_e32 v75, v75, v181
	v_lshlrev_b32_e32 v178, 16, v173
	v_and_b32_e32 v173, 0xffff0000, v173
	v_lshlrev_b32_e32 v179, 16, v177
	v_and_b32_e32 v177, 0xffff0000, v177
	v_mul_f32_e32 v76, 0xbfb8aa3b, v76
	v_mul_f32_e32 v77, 0xbfb8aa3b, v77
	v_mul_f32_e32 v180, 0xbfb8aa3b, v179
	v_mul_f32_e32 v181, 0xbfb8aa3b, v177
	v_exp_f32_e32 v76, v76
	v_exp_f32_e32 v77, v77
	v_exp_f32_e32 v180, v180
	v_exp_f32_e32 v181, v181
	v_add_f32_e32 v76, 1.0, v76
	v_add_f32_e32 v77, 1.0, v77
	v_add_f32_e32 v180, 1.0, v180
	v_add_f32_e32 v181, 1.0, v181
	v_rcp_f32_e32 v76, v76
	v_rcp_f32_e32 v77, v77
	v_rcp_f32_e32 v180, v180
	v_rcp_f32_e32 v181, v181
	v_mul_f32_e32 v76, v76, v178
	v_mul_f32_e32 v77, v77, v173
	v_mul_f32_e32 v180, v180, v179
	v_mul_f32_e32 v181, v181, v177
	v_mul_f32_e32 v76, v76, v180
	v_mul_f32_e32 v77, v77, v181
	v_cvt_pk_bf16_f32 v78, v78, v79
	v_cvt_pk_bf16_f32 v79, v80, v81
	v_cvt_pk_bf16_f32 v80, v74, v75
	v_cvt_pk_bf16_f32 v81, v76, v77
	global_store_dwordx4 v[146:147], v[78:81], off
	global_load_dwordx4 v[170:173], v[142:143], off offset:256
	global_load_dwordx4 v[174:177], v[144:145], off offset:256
	s_waitcnt vmcnt(6)
	v_lshlrev_b32_e32 v178, 16, v154
	v_and_b32_e32 v154, 0xffff0000, v154
	v_lshlrev_b32_e32 v179, 16, v158
	v_and_b32_e32 v158, 0xffff0000, v158
	v_mul_f32_e32 v70, 0xbfb8aa3b, v70
	v_mul_f32_e32 v71, 0xbfb8aa3b, v71
	v_mul_f32_e32 v180, 0xbfb8aa3b, v179
	v_mul_f32_e32 v181, 0xbfb8aa3b, v158
	v_exp_f32_e32 v70, v70
	v_exp_f32_e32 v71, v71
	v_exp_f32_e32 v180, v180
	v_exp_f32_e32 v181, v181
	v_add_f32_e32 v70, 1.0, v70
	v_add_f32_e32 v71, 1.0, v71
	v_add_f32_e32 v180, 1.0, v180
	v_add_f32_e32 v181, 1.0, v181
	v_rcp_f32_e32 v70, v70
	v_rcp_f32_e32 v71, v71
	v_rcp_f32_e32 v180, v180
	v_rcp_f32_e32 v181, v181
	v_mul_f32_e32 v70, v70, v178
	v_mul_f32_e32 v71, v71, v154
	v_mul_f32_e32 v180, v180, v179
	v_mul_f32_e32 v181, v181, v158
	v_mul_f32_e32 v70, v70, v180
	v_mul_f32_e32 v71, v71, v181
	v_lshlrev_b32_e32 v178, 16, v155
	v_and_b32_e32 v155, 0xffff0000, v155
	v_lshlrev_b32_e32 v179, 16, v159
	v_and_b32_e32 v159, 0xffff0000, v159
	v_mul_f32_e32 v72, 0xbfb8aa3b, v72
	v_mul_f32_e32 v73, 0xbfb8aa3b, v73
	v_mul_f32_e32 v180, 0xbfb8aa3b, v179
	v_mul_f32_e32 v181, 0xbfb8aa3b, v159
	v_exp_f32_e32 v72, v72
	v_exp_f32_e32 v73, v73
	v_exp_f32_e32 v180, v180
	v_exp_f32_e32 v181, v181
	v_add_f32_e32 v72, 1.0, v72
	v_add_f32_e32 v73, 1.0, v73
	v_add_f32_e32 v180, 1.0, v180
	v_add_f32_e32 v181, 1.0, v181
	v_rcp_f32_e32 v72, v72
	v_rcp_f32_e32 v73, v73
	v_rcp_f32_e32 v180, v180
	v_rcp_f32_e32 v181, v181
	v_mul_f32_e32 v72, v72, v178
	v_mul_f32_e32 v73, v73, v155
	v_mul_f32_e32 v180, v180, v179
	v_mul_f32_e32 v181, v181, v159
	v_mul_f32_e32 v72, v72, v180
	v_mul_f32_e32 v73, v73, v181
	v_lshlrev_b32_e32 v178, 16, v156
	v_and_b32_e32 v156, 0xffff0000, v156
	v_lshlrev_b32_e32 v179, 16, v160
	v_and_b32_e32 v160, 0xffff0000, v160
	v_mul_f32_e32 v66, 0xbfb8aa3b, v66
	v_mul_f32_e32 v67, 0xbfb8aa3b, v67
	v_mul_f32_e32 v180, 0xbfb8aa3b, v179
	v_mul_f32_e32 v181, 0xbfb8aa3b, v160
	v_exp_f32_e32 v66, v66
	v_exp_f32_e32 v67, v67
	v_exp_f32_e32 v180, v180
	v_exp_f32_e32 v181, v181
	v_add_f32_e32 v66, 1.0, v66
	v_add_f32_e32 v67, 1.0, v67
	v_add_f32_e32 v180, 1.0, v180
	v_add_f32_e32 v181, 1.0, v181
	v_rcp_f32_e32 v66, v66
	v_rcp_f32_e32 v67, v67
	v_rcp_f32_e32 v180, v180
	v_rcp_f32_e32 v181, v181
	v_mul_f32_e32 v66, v66, v178
	v_mul_f32_e32 v67, v67, v156
	v_mul_f32_e32 v180, v180, v179
	v_mul_f32_e32 v181, v181, v160
	v_mul_f32_e32 v66, v66, v180
	v_mul_f32_e32 v67, v67, v181
	v_lshlrev_b32_e32 v178, 16, v157
	v_and_b32_e32 v157, 0xffff0000, v157
	v_lshlrev_b32_e32 v179, 16, v161
	v_and_b32_e32 v161, 0xffff0000, v161
	v_mul_f32_e32 v68, 0xbfb8aa3b, v68
	v_mul_f32_e32 v69, 0xbfb8aa3b, v69
	v_mul_f32_e32 v180, 0xbfb8aa3b, v179
	v_mul_f32_e32 v181, 0xbfb8aa3b, v161
	v_exp_f32_e32 v68, v68
	v_exp_f32_e32 v69, v69
	v_exp_f32_e32 v180, v180
	v_exp_f32_e32 v181, v181
	v_add_f32_e32 v68, 1.0, v68
	v_add_f32_e32 v69, 1.0, v69
	v_add_f32_e32 v180, 1.0, v180
	v_add_f32_e32 v181, 1.0, v181
	v_rcp_f32_e32 v68, v68
	v_rcp_f32_e32 v69, v69
	v_rcp_f32_e32 v180, v180
	v_rcp_f32_e32 v181, v181
	v_mul_f32_e32 v68, v68, v178
	v_mul_f32_e32 v69, v69, v157
	v_mul_f32_e32 v180, v180, v179
	v_mul_f32_e32 v181, v181, v161
	v_mul_f32_e32 v68, v68, v180
	v_mul_f32_e32 v69, v69, v181
	v_cvt_pk_bf16_f32 v70, v70, v71
	v_cvt_pk_bf16_f32 v71, v72, v73
	v_cvt_pk_bf16_f32 v72, v66, v67
	v_cvt_pk_bf16_f32 v73, v68, v69
	global_store_dwordx4 v[146:147], v[70:73], off offset:256
	s_mov_b64 s[58:59], 0xa0000
	v_lshl_add_u64 v[146:147], v[146:147], 0, s[58:59]
	s_mov_b64 s[58:59], 0x8000
	v_lshl_add_u64 v[142:143], v[142:143], 0, s[58:59]
	s_mov_b64 s[58:59], 0x4000
	v_lshl_add_u64 v[144:145], v[144:145], 0, s[58:59]
	global_load_dwordx4 v[154:157], v[142:143], off
	global_load_dwordx4 v[158:161], v[144:145], off
	s_waitcnt vmcnt(6)
	v_lshlrev_b32_e32 v178, 16, v162
	v_and_b32_e32 v162, 0xffff0000, v162
	v_lshlrev_b32_e32 v179, 16, v166
	v_and_b32_e32 v166, 0xffff0000, v166
	v_mul_f32_e32 v62, 0xbfb8aa3b, v62
	v_mul_f32_e32 v63, 0xbfb8aa3b, v63
	v_mul_f32_e32 v180, 0xbfb8aa3b, v179
	v_mul_f32_e32 v181, 0xbfb8aa3b, v166
	v_exp_f32_e32 v62, v62
	v_exp_f32_e32 v63, v63
	v_exp_f32_e32 v180, v180
	v_exp_f32_e32 v181, v181
	v_add_f32_e32 v62, 1.0, v62
	v_add_f32_e32 v63, 1.0, v63
	v_add_f32_e32 v180, 1.0, v180
	v_add_f32_e32 v181, 1.0, v181
	v_rcp_f32_e32 v62, v62
	v_rcp_f32_e32 v63, v63
	v_rcp_f32_e32 v180, v180
	v_rcp_f32_e32 v181, v181
	v_mul_f32_e32 v62, v62, v178
	v_mul_f32_e32 v63, v63, v162
	v_mul_f32_e32 v180, v180, v179
	v_mul_f32_e32 v181, v181, v166
	v_mul_f32_e32 v62, v62, v180
	v_mul_f32_e32 v63, v63, v181
	v_lshlrev_b32_e32 v178, 16, v163
	v_and_b32_e32 v163, 0xffff0000, v163
	v_lshlrev_b32_e32 v179, 16, v167
	v_and_b32_e32 v167, 0xffff0000, v167
	v_mul_f32_e32 v64, 0xbfb8aa3b, v64
	v_mul_f32_e32 v65, 0xbfb8aa3b, v65
	v_mul_f32_e32 v180, 0xbfb8aa3b, v179
	v_mul_f32_e32 v181, 0xbfb8aa3b, v167
	v_exp_f32_e32 v64, v64
	v_exp_f32_e32 v65, v65
	v_exp_f32_e32 v180, v180
	v_exp_f32_e32 v181, v181
	v_add_f32_e32 v64, 1.0, v64
	v_add_f32_e32 v65, 1.0, v65
	v_add_f32_e32 v180, 1.0, v180
	v_add_f32_e32 v181, 1.0, v181
	v_rcp_f32_e32 v64, v64
	v_rcp_f32_e32 v65, v65
	v_rcp_f32_e32 v180, v180
	v_rcp_f32_e32 v181, v181
	v_mul_f32_e32 v64, v64, v178
	v_mul_f32_e32 v65, v65, v163
	v_mul_f32_e32 v180, v180, v179
	v_mul_f32_e32 v181, v181, v167
	v_mul_f32_e32 v64, v64, v180
	v_mul_f32_e32 v65, v65, v181
	v_lshlrev_b32_e32 v178, 16, v164
	v_and_b32_e32 v164, 0xffff0000, v164
	v_lshlrev_b32_e32 v179, 16, v168
	v_and_b32_e32 v168, 0xffff0000, v168
	v_mul_f32_e32 v58, 0xbfb8aa3b, v58
	v_mul_f32_e32 v59, 0xbfb8aa3b, v59
	v_mul_f32_e32 v180, 0xbfb8aa3b, v179
	v_mul_f32_e32 v181, 0xbfb8aa3b, v168
	v_exp_f32_e32 v58, v58
	v_exp_f32_e32 v59, v59
	v_exp_f32_e32 v180, v180
	v_exp_f32_e32 v181, v181
	v_add_f32_e32 v58, 1.0, v58
	v_add_f32_e32 v59, 1.0, v59
	v_add_f32_e32 v180, 1.0, v180
	v_add_f32_e32 v181, 1.0, v181
	v_rcp_f32_e32 v58, v58
	v_rcp_f32_e32 v59, v59
	v_rcp_f32_e32 v180, v180
	v_rcp_f32_e32 v181, v181
	v_mul_f32_e32 v58, v58, v178
	v_mul_f32_e32 v59, v59, v164
	v_mul_f32_e32 v180, v180, v179
	v_mul_f32_e32 v181, v181, v168
	v_mul_f32_e32 v58, v58, v180
	v_mul_f32_e32 v59, v59, v181
	v_lshlrev_b32_e32 v178, 16, v165
	v_and_b32_e32 v165, 0xffff0000, v165
	v_lshlrev_b32_e32 v179, 16, v169
	v_and_b32_e32 v169, 0xffff0000, v169
	v_mul_f32_e32 v60, 0xbfb8aa3b, v60
	v_mul_f32_e32 v61, 0xbfb8aa3b, v61
	v_mul_f32_e32 v180, 0xbfb8aa3b, v179
	v_mul_f32_e32 v181, 0xbfb8aa3b, v169
	v_exp_f32_e32 v60, v60
	v_exp_f32_e32 v61, v61
	v_exp_f32_e32 v180, v180
	v_exp_f32_e32 v181, v181
	v_add_f32_e32 v60, 1.0, v60
	v_add_f32_e32 v61, 1.0, v61
	v_add_f32_e32 v180, 1.0, v180
	v_add_f32_e32 v181, 1.0, v181
	v_rcp_f32_e32 v60, v60
	v_rcp_f32_e32 v61, v61
	v_rcp_f32_e32 v180, v180
	v_rcp_f32_e32 v181, v181
	v_mul_f32_e32 v60, v60, v178
	v_mul_f32_e32 v61, v61, v165
	v_mul_f32_e32 v180, v180, v179
	v_mul_f32_e32 v181, v181, v169
	v_mul_f32_e32 v60, v60, v180
	v_mul_f32_e32 v61, v61, v181
	v_cvt_pk_bf16_f32 v62, v62, v63
	v_cvt_pk_bf16_f32 v63, v64, v65
	v_cvt_pk_bf16_f32 v64, v58, v59
	v_cvt_pk_bf16_f32 v65, v60, v61
	global_store_dwordx4 v[146:147], v[62:65], off
	global_load_dwordx4 v[162:165], v[142:143], off offset:256
	global_load_dwordx4 v[166:169], v[144:145], off offset:256
	s_waitcnt vmcnt(6)
	v_lshlrev_b32_e32 v178, 16, v170
	v_and_b32_e32 v170, 0xffff0000, v170
	v_lshlrev_b32_e32 v179, 16, v174
	v_and_b32_e32 v174, 0xffff0000, v174
	v_mul_f32_e32 v54, 0xbfb8aa3b, v54
	v_mul_f32_e32 v55, 0xbfb8aa3b, v55
	v_mul_f32_e32 v180, 0xbfb8aa3b, v179
	v_mul_f32_e32 v181, 0xbfb8aa3b, v174
	v_exp_f32_e32 v54, v54
	v_exp_f32_e32 v55, v55
	v_exp_f32_e32 v180, v180
	v_exp_f32_e32 v181, v181
	v_add_f32_e32 v54, 1.0, v54
	v_add_f32_e32 v55, 1.0, v55
	v_add_f32_e32 v180, 1.0, v180
	v_add_f32_e32 v181, 1.0, v181
	v_rcp_f32_e32 v54, v54
	v_rcp_f32_e32 v55, v55
	v_rcp_f32_e32 v180, v180
	v_rcp_f32_e32 v181, v181
	v_mul_f32_e32 v54, v54, v178
	v_mul_f32_e32 v55, v55, v170
	v_mul_f32_e32 v180, v180, v179
	v_mul_f32_e32 v181, v181, v174
	v_mul_f32_e32 v54, v54, v180
	v_mul_f32_e32 v55, v55, v181
	v_lshlrev_b32_e32 v178, 16, v171
	v_and_b32_e32 v171, 0xffff0000, v171
	v_lshlrev_b32_e32 v179, 16, v175
	v_and_b32_e32 v175, 0xffff0000, v175
	v_mul_f32_e32 v56, 0xbfb8aa3b, v56
	v_mul_f32_e32 v57, 0xbfb8aa3b, v57
	v_mul_f32_e32 v180, 0xbfb8aa3b, v179
	v_mul_f32_e32 v181, 0xbfb8aa3b, v175
	v_exp_f32_e32 v56, v56
	v_exp_f32_e32 v57, v57
	v_exp_f32_e32 v180, v180
	v_exp_f32_e32 v181, v181
	v_add_f32_e32 v56, 1.0, v56
	v_add_f32_e32 v57, 1.0, v57
	v_add_f32_e32 v180, 1.0, v180
	v_add_f32_e32 v181, 1.0, v181
	v_rcp_f32_e32 v56, v56
	v_rcp_f32_e32 v57, v57
	v_rcp_f32_e32 v180, v180
	v_rcp_f32_e32 v181, v181
	v_mul_f32_e32 v56, v56, v178
	v_mul_f32_e32 v57, v57, v171
	v_mul_f32_e32 v180, v180, v179
	v_mul_f32_e32 v181, v181, v175
	v_mul_f32_e32 v56, v56, v180
	v_mul_f32_e32 v57, v57, v181
	v_lshlrev_b32_e32 v178, 16, v172
	v_and_b32_e32 v172, 0xffff0000, v172
	v_lshlrev_b32_e32 v179, 16, v176
	v_and_b32_e32 v176, 0xffff0000, v176
	v_mul_f32_e32 v50, 0xbfb8aa3b, v50
	v_mul_f32_e32 v51, 0xbfb8aa3b, v51
	v_mul_f32_e32 v180, 0xbfb8aa3b, v179
	v_mul_f32_e32 v181, 0xbfb8aa3b, v176
	v_exp_f32_e32 v50, v50
	v_exp_f32_e32 v51, v51
	v_exp_f32_e32 v180, v180
	v_exp_f32_e32 v181, v181
	v_add_f32_e32 v50, 1.0, v50
	v_add_f32_e32 v51, 1.0, v51
	v_add_f32_e32 v180, 1.0, v180
	v_add_f32_e32 v181, 1.0, v181
	v_rcp_f32_e32 v50, v50
	v_rcp_f32_e32 v51, v51
	v_rcp_f32_e32 v180, v180
	v_rcp_f32_e32 v181, v181
	v_mul_f32_e32 v50, v50, v178
	v_mul_f32_e32 v51, v51, v172
	v_mul_f32_e32 v180, v180, v179
	v_mul_f32_e32 v181, v181, v176
	v_mul_f32_e32 v50, v50, v180
	v_mul_f32_e32 v51, v51, v181
	v_lshlrev_b32_e32 v178, 16, v173
	v_and_b32_e32 v173, 0xffff0000, v173
	v_lshlrev_b32_e32 v179, 16, v177
	v_and_b32_e32 v177, 0xffff0000, v177
	v_mul_f32_e32 v52, 0xbfb8aa3b, v52
	v_mul_f32_e32 v53, 0xbfb8aa3b, v53
	v_mul_f32_e32 v180, 0xbfb8aa3b, v179
	v_mul_f32_e32 v181, 0xbfb8aa3b, v177
	v_exp_f32_e32 v52, v52
	v_exp_f32_e32 v53, v53
	v_exp_f32_e32 v180, v180
	v_exp_f32_e32 v181, v181
	v_add_f32_e32 v52, 1.0, v52
	v_add_f32_e32 v53, 1.0, v53
	v_add_f32_e32 v180, 1.0, v180
	v_add_f32_e32 v181, 1.0, v181
	v_rcp_f32_e32 v52, v52
	v_rcp_f32_e32 v53, v53
	v_rcp_f32_e32 v180, v180
	v_rcp_f32_e32 v181, v181
	v_mul_f32_e32 v52, v52, v178
	v_mul_f32_e32 v53, v53, v173
	v_mul_f32_e32 v180, v180, v179
	v_mul_f32_e32 v181, v181, v177
	v_mul_f32_e32 v52, v52, v180
	v_mul_f32_e32 v53, v53, v181
	v_cvt_pk_bf16_f32 v54, v54, v55
	v_cvt_pk_bf16_f32 v55, v56, v57
	v_cvt_pk_bf16_f32 v56, v50, v51
	v_cvt_pk_bf16_f32 v57, v52, v53
	global_store_dwordx4 v[146:147], v[54:57], off offset:256
	s_mov_b64 s[58:59], 0x20000
	v_lshl_add_u64 v[146:147], v[146:147], 0, s[58:59]
	s_mov_b64 s[58:59], 0x8000
	v_lshl_add_u64 v[142:143], v[142:143], 0, s[58:59]
	s_mov_b64 s[58:59], 0x4000
	v_lshl_add_u64 v[144:145], v[144:145], 0, s[58:59]
	global_load_dwordx4 v[170:173], v[142:143], off
	global_load_dwordx4 v[174:177], v[144:145], off
	s_waitcnt vmcnt(6)
	v_lshlrev_b32_e32 v178, 16, v154
	v_and_b32_e32 v154, 0xffff0000, v154
	v_lshlrev_b32_e32 v179, 16, v158
	v_and_b32_e32 v158, 0xffff0000, v158
	v_mul_f32_e32 v46, 0xbfb8aa3b, v46
	v_mul_f32_e32 v47, 0xbfb8aa3b, v47
	v_mul_f32_e32 v180, 0xbfb8aa3b, v179
	v_mul_f32_e32 v181, 0xbfb8aa3b, v158
	v_exp_f32_e32 v46, v46
	v_exp_f32_e32 v47, v47
	v_exp_f32_e32 v180, v180
	v_exp_f32_e32 v181, v181
	v_add_f32_e32 v46, 1.0, v46
	v_add_f32_e32 v47, 1.0, v47
	v_add_f32_e32 v180, 1.0, v180
	v_add_f32_e32 v181, 1.0, v181
	v_rcp_f32_e32 v46, v46
	v_rcp_f32_e32 v47, v47
	v_rcp_f32_e32 v180, v180
	v_rcp_f32_e32 v181, v181
	v_mul_f32_e32 v46, v46, v178
	v_mul_f32_e32 v47, v47, v154
	v_mul_f32_e32 v180, v180, v179
	v_mul_f32_e32 v181, v181, v158
	v_mul_f32_e32 v46, v46, v180
	v_mul_f32_e32 v47, v47, v181
	v_lshlrev_b32_e32 v178, 16, v155
	v_and_b32_e32 v155, 0xffff0000, v155
	v_lshlrev_b32_e32 v179, 16, v159
	v_and_b32_e32 v159, 0xffff0000, v159
	v_mul_f32_e32 v48, 0xbfb8aa3b, v48
	v_mul_f32_e32 v49, 0xbfb8aa3b, v49
	v_mul_f32_e32 v180, 0xbfb8aa3b, v179
	v_mul_f32_e32 v181, 0xbfb8aa3b, v159
	v_exp_f32_e32 v48, v48
	v_exp_f32_e32 v49, v49
	v_exp_f32_e32 v180, v180
	v_exp_f32_e32 v181, v181
	v_add_f32_e32 v48, 1.0, v48
	v_add_f32_e32 v49, 1.0, v49
	v_add_f32_e32 v180, 1.0, v180
	v_add_f32_e32 v181, 1.0, v181
	v_rcp_f32_e32 v48, v48
	v_rcp_f32_e32 v49, v49
	v_rcp_f32_e32 v180, v180
	v_rcp_f32_e32 v181, v181
	v_mul_f32_e32 v48, v48, v178
	v_mul_f32_e32 v49, v49, v155
	v_mul_f32_e32 v180, v180, v179
	v_mul_f32_e32 v181, v181, v159
	v_mul_f32_e32 v48, v48, v180
	v_mul_f32_e32 v49, v49, v181
	v_lshlrev_b32_e32 v178, 16, v156
	v_and_b32_e32 v156, 0xffff0000, v156
	v_lshlrev_b32_e32 v179, 16, v160
	v_and_b32_e32 v160, 0xffff0000, v160
	v_mul_f32_e32 v42, 0xbfb8aa3b, v42
	v_mul_f32_e32 v43, 0xbfb8aa3b, v43
	v_mul_f32_e32 v180, 0xbfb8aa3b, v179
	v_mul_f32_e32 v181, 0xbfb8aa3b, v160
	v_exp_f32_e32 v42, v42
	v_exp_f32_e32 v43, v43
	v_exp_f32_e32 v180, v180
	v_exp_f32_e32 v181, v181
	v_add_f32_e32 v42, 1.0, v42
	v_add_f32_e32 v43, 1.0, v43
	v_add_f32_e32 v180, 1.0, v180
	v_add_f32_e32 v181, 1.0, v181
	v_rcp_f32_e32 v42, v42
	v_rcp_f32_e32 v43, v43
	v_rcp_f32_e32 v180, v180
	v_rcp_f32_e32 v181, v181
	v_mul_f32_e32 v42, v42, v178
	v_mul_f32_e32 v43, v43, v156
	v_mul_f32_e32 v180, v180, v179
	v_mul_f32_e32 v181, v181, v160
	v_mul_f32_e32 v42, v42, v180
	v_mul_f32_e32 v43, v43, v181
	v_lshlrev_b32_e32 v178, 16, v157
	v_and_b32_e32 v157, 0xffff0000, v157
	v_lshlrev_b32_e32 v179, 16, v161
	v_and_b32_e32 v161, 0xffff0000, v161
	v_mul_f32_e32 v44, 0xbfb8aa3b, v44
	v_mul_f32_e32 v45, 0xbfb8aa3b, v45
	v_mul_f32_e32 v180, 0xbfb8aa3b, v179
	v_mul_f32_e32 v181, 0xbfb8aa3b, v161
	v_exp_f32_e32 v44, v44
	v_exp_f32_e32 v45, v45
	v_exp_f32_e32 v180, v180
	v_exp_f32_e32 v181, v181
	v_add_f32_e32 v44, 1.0, v44
	v_add_f32_e32 v45, 1.0, v45
	v_add_f32_e32 v180, 1.0, v180
	v_add_f32_e32 v181, 1.0, v181
	v_rcp_f32_e32 v44, v44
	v_rcp_f32_e32 v45, v45
	v_rcp_f32_e32 v180, v180
	v_rcp_f32_e32 v181, v181
	v_mul_f32_e32 v44, v44, v178
	v_mul_f32_e32 v45, v45, v157
	v_mul_f32_e32 v180, v180, v179
	v_mul_f32_e32 v181, v181, v161
	v_mul_f32_e32 v44, v44, v180
	v_mul_f32_e32 v45, v45, v181
	v_cvt_pk_bf16_f32 v46, v46, v47
	v_cvt_pk_bf16_f32 v47, v48, v49
	v_cvt_pk_bf16_f32 v48, v42, v43
	v_cvt_pk_bf16_f32 v49, v44, v45
	global_store_dwordx4 v[146:147], v[46:49], off
	global_load_dwordx4 v[154:157], v[142:143], off offset:256
	global_load_dwordx4 v[158:161], v[144:145], off offset:256
	s_waitcnt vmcnt(6)
	v_lshlrev_b32_e32 v178, 16, v162
	v_and_b32_e32 v162, 0xffff0000, v162
	v_lshlrev_b32_e32 v179, 16, v166
	v_and_b32_e32 v166, 0xffff0000, v166
	v_mul_f32_e32 v38, 0xbfb8aa3b, v38
	v_mul_f32_e32 v39, 0xbfb8aa3b, v39
	v_mul_f32_e32 v180, 0xbfb8aa3b, v179
	v_mul_f32_e32 v181, 0xbfb8aa3b, v166
	v_exp_f32_e32 v38, v38
	v_exp_f32_e32 v39, v39
	v_exp_f32_e32 v180, v180
	v_exp_f32_e32 v181, v181
	v_add_f32_e32 v38, 1.0, v38
	v_add_f32_e32 v39, 1.0, v39
	v_add_f32_e32 v180, 1.0, v180
	v_add_f32_e32 v181, 1.0, v181
	v_rcp_f32_e32 v38, v38
	v_rcp_f32_e32 v39, v39
	v_rcp_f32_e32 v180, v180
	v_rcp_f32_e32 v181, v181
	v_mul_f32_e32 v38, v38, v178
	v_mul_f32_e32 v39, v39, v162
	v_mul_f32_e32 v180, v180, v179
	v_mul_f32_e32 v181, v181, v166
	v_mul_f32_e32 v38, v38, v180
	v_mul_f32_e32 v39, v39, v181
	v_lshlrev_b32_e32 v178, 16, v163
	v_and_b32_e32 v163, 0xffff0000, v163
	v_lshlrev_b32_e32 v179, 16, v167
	v_and_b32_e32 v167, 0xffff0000, v167
	v_mul_f32_e32 v40, 0xbfb8aa3b, v40
	v_mul_f32_e32 v41, 0xbfb8aa3b, v41
	v_mul_f32_e32 v180, 0xbfb8aa3b, v179
	v_mul_f32_e32 v181, 0xbfb8aa3b, v167
	v_exp_f32_e32 v40, v40
	v_exp_f32_e32 v41, v41
	v_exp_f32_e32 v180, v180
	v_exp_f32_e32 v181, v181
	v_add_f32_e32 v40, 1.0, v40
	v_add_f32_e32 v41, 1.0, v41
	v_add_f32_e32 v180, 1.0, v180
	v_add_f32_e32 v181, 1.0, v181
	v_rcp_f32_e32 v40, v40
	v_rcp_f32_e32 v41, v41
	v_rcp_f32_e32 v180, v180
	v_rcp_f32_e32 v181, v181
	v_mul_f32_e32 v40, v40, v178
	v_mul_f32_e32 v41, v41, v163
	v_mul_f32_e32 v180, v180, v179
	v_mul_f32_e32 v181, v181, v167
	v_mul_f32_e32 v40, v40, v180
	v_mul_f32_e32 v41, v41, v181
	v_lshlrev_b32_e32 v178, 16, v164
	v_and_b32_e32 v164, 0xffff0000, v164
	v_lshlrev_b32_e32 v179, 16, v168
	v_and_b32_e32 v168, 0xffff0000, v168
	v_mul_f32_e32 v34, 0xbfb8aa3b, v34
	v_mul_f32_e32 v35, 0xbfb8aa3b, v35
	v_mul_f32_e32 v180, 0xbfb8aa3b, v179
	v_mul_f32_e32 v181, 0xbfb8aa3b, v168
	v_exp_f32_e32 v34, v34
	v_exp_f32_e32 v35, v35
	v_exp_f32_e32 v180, v180
	v_exp_f32_e32 v181, v181
	v_add_f32_e32 v34, 1.0, v34
	v_add_f32_e32 v35, 1.0, v35
	v_add_f32_e32 v180, 1.0, v180
	v_add_f32_e32 v181, 1.0, v181
	v_rcp_f32_e32 v34, v34
	v_rcp_f32_e32 v35, v35
	v_rcp_f32_e32 v180, v180
	v_rcp_f32_e32 v181, v181
	v_mul_f32_e32 v34, v34, v178
	v_mul_f32_e32 v35, v35, v164
	v_mul_f32_e32 v180, v180, v179
	v_mul_f32_e32 v181, v181, v168
	v_mul_f32_e32 v34, v34, v180
	v_mul_f32_e32 v35, v35, v181
	v_lshlrev_b32_e32 v178, 16, v165
	v_and_b32_e32 v165, 0xffff0000, v165
	v_lshlrev_b32_e32 v179, 16, v169
	v_and_b32_e32 v169, 0xffff0000, v169
	v_mul_f32_e32 v36, 0xbfb8aa3b, v36
	v_mul_f32_e32 v37, 0xbfb8aa3b, v37
	v_mul_f32_e32 v180, 0xbfb8aa3b, v179
	v_mul_f32_e32 v181, 0xbfb8aa3b, v169
	v_exp_f32_e32 v36, v36
	v_exp_f32_e32 v37, v37
	v_exp_f32_e32 v180, v180
	v_exp_f32_e32 v181, v181
	v_add_f32_e32 v36, 1.0, v36
	v_add_f32_e32 v37, 1.0, v37
	v_add_f32_e32 v180, 1.0, v180
	v_add_f32_e32 v181, 1.0, v181
	v_rcp_f32_e32 v36, v36
	v_rcp_f32_e32 v37, v37
	v_rcp_f32_e32 v180, v180
	v_rcp_f32_e32 v181, v181
	v_mul_f32_e32 v36, v36, v178
	v_mul_f32_e32 v37, v37, v165
	v_mul_f32_e32 v180, v180, v179
	v_mul_f32_e32 v181, v181, v169
	v_mul_f32_e32 v36, v36, v180
	v_mul_f32_e32 v37, v37, v181
	v_cvt_pk_bf16_f32 v38, v38, v39
	v_cvt_pk_bf16_f32 v39, v40, v41
	v_cvt_pk_bf16_f32 v40, v34, v35
	v_cvt_pk_bf16_f32 v41, v36, v37
	global_store_dwordx4 v[146:147], v[38:41], off offset:256
	s_mov_b64 s[58:59], 0x20000
	v_lshl_add_u64 v[146:147], v[146:147], 0, s[58:59]
	s_mov_b64 s[58:59], 0x8000
	v_lshl_add_u64 v[142:143], v[142:143], 0, s[58:59]
	s_mov_b64 s[58:59], 0x4000
	v_lshl_add_u64 v[144:145], v[144:145], 0, s[58:59]
	global_load_dwordx4 v[162:165], v[142:143], off
	global_load_dwordx4 v[166:169], v[144:145], off
	s_waitcnt vmcnt(6)
	v_lshlrev_b32_e32 v178, 16, v170
	v_and_b32_e32 v170, 0xffff0000, v170
	v_lshlrev_b32_e32 v179, 16, v174
	v_and_b32_e32 v174, 0xffff0000, v174
	v_mul_f32_e32 v30, 0xbfb8aa3b, v30
	v_mul_f32_e32 v31, 0xbfb8aa3b, v31
	v_mul_f32_e32 v180, 0xbfb8aa3b, v179
	v_mul_f32_e32 v181, 0xbfb8aa3b, v174
	v_exp_f32_e32 v30, v30
	v_exp_f32_e32 v31, v31
	v_exp_f32_e32 v180, v180
	v_exp_f32_e32 v181, v181
	v_add_f32_e32 v30, 1.0, v30
	v_add_f32_e32 v31, 1.0, v31
	v_add_f32_e32 v180, 1.0, v180
	v_add_f32_e32 v181, 1.0, v181
	v_rcp_f32_e32 v30, v30
	v_rcp_f32_e32 v31, v31
	v_rcp_f32_e32 v180, v180
	v_rcp_f32_e32 v181, v181
	v_mul_f32_e32 v30, v30, v178
	v_mul_f32_e32 v31, v31, v170
	v_mul_f32_e32 v180, v180, v179
	v_mul_f32_e32 v181, v181, v174
	v_mul_f32_e32 v30, v30, v180
	v_mul_f32_e32 v31, v31, v181
	v_lshlrev_b32_e32 v178, 16, v171
	v_and_b32_e32 v171, 0xffff0000, v171
	v_lshlrev_b32_e32 v179, 16, v175
	v_and_b32_e32 v175, 0xffff0000, v175
	v_mul_f32_e32 v32, 0xbfb8aa3b, v32
	v_mul_f32_e32 v33, 0xbfb8aa3b, v33
	v_mul_f32_e32 v180, 0xbfb8aa3b, v179
	v_mul_f32_e32 v181, 0xbfb8aa3b, v175
	v_exp_f32_e32 v32, v32
	v_exp_f32_e32 v33, v33
	v_exp_f32_e32 v180, v180
	v_exp_f32_e32 v181, v181
	v_add_f32_e32 v32, 1.0, v32
	v_add_f32_e32 v33, 1.0, v33
	v_add_f32_e32 v180, 1.0, v180
	v_add_f32_e32 v181, 1.0, v181
	v_rcp_f32_e32 v32, v32
	v_rcp_f32_e32 v33, v33
	v_rcp_f32_e32 v180, v180
	v_rcp_f32_e32 v181, v181
	v_mul_f32_e32 v32, v32, v178
	v_mul_f32_e32 v33, v33, v171
	v_mul_f32_e32 v180, v180, v179
	v_mul_f32_e32 v181, v181, v175
	v_mul_f32_e32 v32, v32, v180
	v_mul_f32_e32 v33, v33, v181
	v_lshlrev_b32_e32 v178, 16, v172
	v_and_b32_e32 v172, 0xffff0000, v172
	v_lshlrev_b32_e32 v179, 16, v176
	v_and_b32_e32 v176, 0xffff0000, v176
	v_mul_f32_e32 v26, 0xbfb8aa3b, v26
	v_mul_f32_e32 v27, 0xbfb8aa3b, v27
	v_mul_f32_e32 v180, 0xbfb8aa3b, v179
	v_mul_f32_e32 v181, 0xbfb8aa3b, v176
	v_exp_f32_e32 v26, v26
	v_exp_f32_e32 v27, v27
	v_exp_f32_e32 v180, v180
	v_exp_f32_e32 v181, v181
	v_add_f32_e32 v26, 1.0, v26
	v_add_f32_e32 v27, 1.0, v27
	v_add_f32_e32 v180, 1.0, v180
	v_add_f32_e32 v181, 1.0, v181
	v_rcp_f32_e32 v26, v26
	v_rcp_f32_e32 v27, v27
	v_rcp_f32_e32 v180, v180
	v_rcp_f32_e32 v181, v181
	v_mul_f32_e32 v26, v26, v178
	v_mul_f32_e32 v27, v27, v172
	v_mul_f32_e32 v180, v180, v179
	v_mul_f32_e32 v181, v181, v176
	v_mul_f32_e32 v26, v26, v180
	v_mul_f32_e32 v27, v27, v181
	v_lshlrev_b32_e32 v178, 16, v173
	v_and_b32_e32 v173, 0xffff0000, v173
	v_lshlrev_b32_e32 v179, 16, v177
	v_and_b32_e32 v177, 0xffff0000, v177
	v_mul_f32_e32 v28, 0xbfb8aa3b, v28
	v_mul_f32_e32 v29, 0xbfb8aa3b, v29
	v_mul_f32_e32 v180, 0xbfb8aa3b, v179
	v_mul_f32_e32 v181, 0xbfb8aa3b, v177
	v_exp_f32_e32 v28, v28
	v_exp_f32_e32 v29, v29
	v_exp_f32_e32 v180, v180
	v_exp_f32_e32 v181, v181
	v_add_f32_e32 v28, 1.0, v28
	v_add_f32_e32 v29, 1.0, v29
	v_add_f32_e32 v180, 1.0, v180
	v_add_f32_e32 v181, 1.0, v181
	v_rcp_f32_e32 v28, v28
	v_rcp_f32_e32 v29, v29
	v_rcp_f32_e32 v180, v180
	v_rcp_f32_e32 v181, v181
	v_mul_f32_e32 v28, v28, v178
	v_mul_f32_e32 v29, v29, v173
	v_mul_f32_e32 v180, v180, v179
	v_mul_f32_e32 v181, v181, v177
	v_mul_f32_e32 v28, v28, v180
	v_mul_f32_e32 v29, v29, v181
	v_cvt_pk_bf16_f32 v30, v30, v31
	v_cvt_pk_bf16_f32 v31, v32, v33
	v_cvt_pk_bf16_f32 v32, v26, v27
	v_cvt_pk_bf16_f32 v33, v28, v29
	global_store_dwordx4 v[146:147], v[30:33], off
	global_load_dwordx4 v[170:173], v[142:143], off offset:256
	global_load_dwordx4 v[174:177], v[144:145], off offset:256
	s_waitcnt vmcnt(6)
	v_lshlrev_b32_e32 v178, 16, v154
	v_and_b32_e32 v154, 0xffff0000, v154
	v_lshlrev_b32_e32 v179, 16, v158
	v_and_b32_e32 v158, 0xffff0000, v158
	v_mul_f32_e32 v22, 0xbfb8aa3b, v22
	v_mul_f32_e32 v23, 0xbfb8aa3b, v23
	v_mul_f32_e32 v180, 0xbfb8aa3b, v179
	v_mul_f32_e32 v181, 0xbfb8aa3b, v158
	v_exp_f32_e32 v22, v22
	v_exp_f32_e32 v23, v23
	v_exp_f32_e32 v180, v180
	v_exp_f32_e32 v181, v181
	v_add_f32_e32 v22, 1.0, v22
	v_add_f32_e32 v23, 1.0, v23
	v_add_f32_e32 v180, 1.0, v180
	v_add_f32_e32 v181, 1.0, v181
	v_rcp_f32_e32 v22, v22
	v_rcp_f32_e32 v23, v23
	v_rcp_f32_e32 v180, v180
	v_rcp_f32_e32 v181, v181
	v_mul_f32_e32 v22, v22, v178
	v_mul_f32_e32 v23, v23, v154
	v_mul_f32_e32 v180, v180, v179
	v_mul_f32_e32 v181, v181, v158
	v_mul_f32_e32 v22, v22, v180
	v_mul_f32_e32 v23, v23, v181
	v_lshlrev_b32_e32 v178, 16, v155
	v_and_b32_e32 v155, 0xffff0000, v155
	v_lshlrev_b32_e32 v179, 16, v159
	v_and_b32_e32 v159, 0xffff0000, v159
	v_mul_f32_e32 v24, 0xbfb8aa3b, v24
	v_mul_f32_e32 v25, 0xbfb8aa3b, v25
	v_mul_f32_e32 v180, 0xbfb8aa3b, v179
	v_mul_f32_e32 v181, 0xbfb8aa3b, v159
	v_exp_f32_e32 v24, v24
	v_exp_f32_e32 v25, v25
	v_exp_f32_e32 v180, v180
	v_exp_f32_e32 v181, v181
	v_add_f32_e32 v24, 1.0, v24
	v_add_f32_e32 v25, 1.0, v25
	v_add_f32_e32 v180, 1.0, v180
	v_add_f32_e32 v181, 1.0, v181
	v_rcp_f32_e32 v24, v24
	v_rcp_f32_e32 v25, v25
	v_rcp_f32_e32 v180, v180
	v_rcp_f32_e32 v181, v181
	v_mul_f32_e32 v24, v24, v178
	v_mul_f32_e32 v25, v25, v155
	v_mul_f32_e32 v180, v180, v179
	v_mul_f32_e32 v181, v181, v159
	v_mul_f32_e32 v24, v24, v180
	v_mul_f32_e32 v25, v25, v181
	v_lshlrev_b32_e32 v178, 16, v156
	v_and_b32_e32 v156, 0xffff0000, v156
	v_lshlrev_b32_e32 v179, 16, v160
	v_and_b32_e32 v160, 0xffff0000, v160
	v_mul_f32_e32 v18, 0xbfb8aa3b, v18
	v_mul_f32_e32 v19, 0xbfb8aa3b, v19
	v_mul_f32_e32 v180, 0xbfb8aa3b, v179
	v_mul_f32_e32 v181, 0xbfb8aa3b, v160
	v_exp_f32_e32 v18, v18
	v_exp_f32_e32 v19, v19
	v_exp_f32_e32 v180, v180
	v_exp_f32_e32 v181, v181
	v_add_f32_e32 v18, 1.0, v18
	v_add_f32_e32 v19, 1.0, v19
	v_add_f32_e32 v180, 1.0, v180
	v_add_f32_e32 v181, 1.0, v181
	v_rcp_f32_e32 v18, v18
	v_rcp_f32_e32 v19, v19
	v_rcp_f32_e32 v180, v180
	v_rcp_f32_e32 v181, v181
	v_mul_f32_e32 v18, v18, v178
	v_mul_f32_e32 v19, v19, v156
	v_mul_f32_e32 v180, v180, v179
	v_mul_f32_e32 v181, v181, v160
	v_mul_f32_e32 v18, v18, v180
	v_mul_f32_e32 v19, v19, v181
	v_lshlrev_b32_e32 v178, 16, v157
	v_and_b32_e32 v157, 0xffff0000, v157
	v_lshlrev_b32_e32 v179, 16, v161
	v_and_b32_e32 v161, 0xffff0000, v161
	v_mul_f32_e32 v20, 0xbfb8aa3b, v20
	v_mul_f32_e32 v21, 0xbfb8aa3b, v21
	v_mul_f32_e32 v180, 0xbfb8aa3b, v179
	v_mul_f32_e32 v181, 0xbfb8aa3b, v161
	v_exp_f32_e32 v20, v20
	v_exp_f32_e32 v21, v21
	v_exp_f32_e32 v180, v180
	v_exp_f32_e32 v181, v181
	v_add_f32_e32 v20, 1.0, v20
	v_add_f32_e32 v21, 1.0, v21
	v_add_f32_e32 v180, 1.0, v180
	v_add_f32_e32 v181, 1.0, v181
	v_rcp_f32_e32 v20, v20
	v_rcp_f32_e32 v21, v21
	v_rcp_f32_e32 v180, v180
	v_rcp_f32_e32 v181, v181
	v_mul_f32_e32 v20, v20, v178
	v_mul_f32_e32 v21, v21, v157
	v_mul_f32_e32 v180, v180, v179
	v_mul_f32_e32 v181, v181, v161
	v_mul_f32_e32 v20, v20, v180
	v_mul_f32_e32 v21, v21, v181
	v_cvt_pk_bf16_f32 v22, v22, v23
	v_cvt_pk_bf16_f32 v23, v24, v25
	v_cvt_pk_bf16_f32 v24, v18, v19
	v_cvt_pk_bf16_f32 v25, v20, v21
	global_store_dwordx4 v[146:147], v[22:25], off offset:256
	s_mov_b64 s[58:59], 0x20000
	v_lshl_add_u64 v[146:147], v[146:147], 0, s[58:59]
	s_waitcnt vmcnt(4)
	v_lshlrev_b32_e32 v178, 16, v162
	v_and_b32_e32 v162, 0xffff0000, v162
	v_lshlrev_b32_e32 v179, 16, v166
	v_and_b32_e32 v166, 0xffff0000, v166
	v_mul_f32_e32 v14, 0xbfb8aa3b, v14
	v_mul_f32_e32 v15, 0xbfb8aa3b, v15
	v_mul_f32_e32 v180, 0xbfb8aa3b, v179
	v_mul_f32_e32 v181, 0xbfb8aa3b, v166
	v_exp_f32_e32 v14, v14
	v_exp_f32_e32 v15, v15
	v_exp_f32_e32 v180, v180
	v_exp_f32_e32 v181, v181
	v_add_f32_e32 v14, 1.0, v14
	v_add_f32_e32 v15, 1.0, v15
	v_add_f32_e32 v180, 1.0, v180
	v_add_f32_e32 v181, 1.0, v181
	v_rcp_f32_e32 v14, v14
	v_rcp_f32_e32 v15, v15
	v_rcp_f32_e32 v180, v180
	v_rcp_f32_e32 v181, v181
	v_mul_f32_e32 v14, v14, v178
	v_mul_f32_e32 v15, v15, v162
	v_mul_f32_e32 v180, v180, v179
	v_mul_f32_e32 v181, v181, v166
	v_mul_f32_e32 v14, v14, v180
	v_mul_f32_e32 v15, v15, v181
	v_lshlrev_b32_e32 v178, 16, v163
	v_and_b32_e32 v163, 0xffff0000, v163
	v_lshlrev_b32_e32 v179, 16, v167
	v_and_b32_e32 v167, 0xffff0000, v167
	v_mul_f32_e32 v16, 0xbfb8aa3b, v16
	v_mul_f32_e32 v17, 0xbfb8aa3b, v17
	v_mul_f32_e32 v180, 0xbfb8aa3b, v179
	v_mul_f32_e32 v181, 0xbfb8aa3b, v167
	v_exp_f32_e32 v16, v16
	v_exp_f32_e32 v17, v17
	v_exp_f32_e32 v180, v180
	v_exp_f32_e32 v181, v181
	v_add_f32_e32 v16, 1.0, v16
	v_add_f32_e32 v17, 1.0, v17
	v_add_f32_e32 v180, 1.0, v180
	v_add_f32_e32 v181, 1.0, v181
	v_rcp_f32_e32 v16, v16
	v_rcp_f32_e32 v17, v17
	v_rcp_f32_e32 v180, v180
	v_rcp_f32_e32 v181, v181
	v_mul_f32_e32 v16, v16, v178
	v_mul_f32_e32 v17, v17, v163
	v_mul_f32_e32 v180, v180, v179
	v_mul_f32_e32 v181, v181, v167
	v_mul_f32_e32 v16, v16, v180
	v_mul_f32_e32 v17, v17, v181
	v_lshlrev_b32_e32 v178, 16, v164
	v_and_b32_e32 v164, 0xffff0000, v164
	v_lshlrev_b32_e32 v179, 16, v168
	v_and_b32_e32 v168, 0xffff0000, v168
	v_mul_f32_e32 v10, 0xbfb8aa3b, v10
	v_mul_f32_e32 v11, 0xbfb8aa3b, v11
	v_mul_f32_e32 v180, 0xbfb8aa3b, v179
	v_mul_f32_e32 v181, 0xbfb8aa3b, v168
	v_exp_f32_e32 v10, v10
	v_exp_f32_e32 v11, v11
	v_exp_f32_e32 v180, v180
	v_exp_f32_e32 v181, v181
	v_add_f32_e32 v10, 1.0, v10
	v_add_f32_e32 v11, 1.0, v11
	v_add_f32_e32 v180, 1.0, v180
	v_add_f32_e32 v181, 1.0, v181
	v_rcp_f32_e32 v10, v10
	v_rcp_f32_e32 v11, v11
	v_rcp_f32_e32 v180, v180
	v_rcp_f32_e32 v181, v181
	v_mul_f32_e32 v10, v10, v178
	v_mul_f32_e32 v11, v11, v164
	v_mul_f32_e32 v180, v180, v179
	v_mul_f32_e32 v181, v181, v168
	v_mul_f32_e32 v10, v10, v180
	v_mul_f32_e32 v11, v11, v181
	v_lshlrev_b32_e32 v178, 16, v165
	v_and_b32_e32 v165, 0xffff0000, v165
	v_lshlrev_b32_e32 v179, 16, v169
	v_and_b32_e32 v169, 0xffff0000, v169
	v_mul_f32_e32 v12, 0xbfb8aa3b, v12
	v_mul_f32_e32 v13, 0xbfb8aa3b, v13
	v_mul_f32_e32 v180, 0xbfb8aa3b, v179
	v_mul_f32_e32 v181, 0xbfb8aa3b, v169
	v_exp_f32_e32 v12, v12
	v_exp_f32_e32 v13, v13
	v_exp_f32_e32 v180, v180
	v_exp_f32_e32 v181, v181
	v_add_f32_e32 v12, 1.0, v12
	v_add_f32_e32 v13, 1.0, v13
	v_add_f32_e32 v180, 1.0, v180
	v_add_f32_e32 v181, 1.0, v181
	v_rcp_f32_e32 v12, v12
	v_rcp_f32_e32 v13, v13
	v_rcp_f32_e32 v180, v180
	v_rcp_f32_e32 v181, v181
	v_mul_f32_e32 v12, v12, v178
	v_mul_f32_e32 v13, v13, v165
	v_mul_f32_e32 v180, v180, v179
	v_mul_f32_e32 v181, v181, v169
	v_mul_f32_e32 v12, v12, v180
	v_mul_f32_e32 v13, v13, v181
	v_cvt_pk_bf16_f32 v14, v14, v15
	v_cvt_pk_bf16_f32 v15, v16, v17
	v_cvt_pk_bf16_f32 v16, v10, v11
	v_cvt_pk_bf16_f32 v17, v12, v13
	global_store_dwordx4 v[146:147], v[14:17], off
	s_waitcnt vmcnt(2)
	v_lshlrev_b32_e32 v178, 16, v170
	v_and_b32_e32 v170, 0xffff0000, v170
	v_lshlrev_b32_e32 v179, 16, v174
	v_and_b32_e32 v174, 0xffff0000, v174
	v_mul_f32_e32 v6, 0xbfb8aa3b, v6
	v_mul_f32_e32 v7, 0xbfb8aa3b, v7
	v_mul_f32_e32 v180, 0xbfb8aa3b, v179
	v_mul_f32_e32 v181, 0xbfb8aa3b, v174
	v_exp_f32_e32 v6, v6
	v_exp_f32_e32 v7, v7
	v_exp_f32_e32 v180, v180
	v_exp_f32_e32 v181, v181
	v_add_f32_e32 v6, 1.0, v6
	v_add_f32_e32 v7, 1.0, v7
	v_add_f32_e32 v180, 1.0, v180
	v_add_f32_e32 v181, 1.0, v181
	v_rcp_f32_e32 v6, v6
	v_rcp_f32_e32 v7, v7
	v_rcp_f32_e32 v180, v180
	v_rcp_f32_e32 v181, v181
	v_mul_f32_e32 v6, v6, v178
	v_mul_f32_e32 v7, v7, v170
	v_mul_f32_e32 v180, v180, v179
	v_mul_f32_e32 v181, v181, v174
	v_mul_f32_e32 v6, v6, v180
	v_mul_f32_e32 v7, v7, v181
	v_lshlrev_b32_e32 v178, 16, v171
	v_and_b32_e32 v171, 0xffff0000, v171
	v_lshlrev_b32_e32 v179, 16, v175
	v_and_b32_e32 v175, 0xffff0000, v175
	v_mul_f32_e32 v8, 0xbfb8aa3b, v8
	v_mul_f32_e32 v9, 0xbfb8aa3b, v9
	v_mul_f32_e32 v180, 0xbfb8aa3b, v179
	v_mul_f32_e32 v181, 0xbfb8aa3b, v175
	v_exp_f32_e32 v8, v8
	v_exp_f32_e32 v9, v9
	v_exp_f32_e32 v180, v180
	v_exp_f32_e32 v181, v181
	v_add_f32_e32 v8, 1.0, v8
	v_add_f32_e32 v9, 1.0, v9
	v_add_f32_e32 v180, 1.0, v180
	v_add_f32_e32 v181, 1.0, v181
	v_rcp_f32_e32 v8, v8
	v_rcp_f32_e32 v9, v9
	v_rcp_f32_e32 v180, v180
	v_rcp_f32_e32 v181, v181
	v_mul_f32_e32 v8, v8, v178
	v_mul_f32_e32 v9, v9, v171
	v_mul_f32_e32 v180, v180, v179
	v_mul_f32_e32 v181, v181, v175
	v_mul_f32_e32 v8, v8, v180
	v_mul_f32_e32 v9, v9, v181
	v_lshlrev_b32_e32 v178, 16, v172
	v_and_b32_e32 v172, 0xffff0000, v172
	v_lshlrev_b32_e32 v179, 16, v176
	v_and_b32_e32 v176, 0xffff0000, v176
	v_mul_f32_e32 v2, 0xbfb8aa3b, v2
	v_mul_f32_e32 v3, 0xbfb8aa3b, v3
	v_mul_f32_e32 v180, 0xbfb8aa3b, v179
	v_mul_f32_e32 v181, 0xbfb8aa3b, v176
	v_exp_f32_e32 v2, v2
	v_exp_f32_e32 v3, v3
	v_exp_f32_e32 v180, v180
	v_exp_f32_e32 v181, v181
	v_add_f32_e32 v2, 1.0, v2
	v_add_f32_e32 v3, 1.0, v3
	v_add_f32_e32 v180, 1.0, v180
	v_add_f32_e32 v181, 1.0, v181
	v_rcp_f32_e32 v2, v2
	v_rcp_f32_e32 v3, v3
	v_rcp_f32_e32 v180, v180
	v_rcp_f32_e32 v181, v181
	v_mul_f32_e32 v2, v2, v178
	v_mul_f32_e32 v3, v3, v172
	v_mul_f32_e32 v180, v180, v179
	v_mul_f32_e32 v181, v181, v176
	v_mul_f32_e32 v2, v2, v180
	v_mul_f32_e32 v3, v3, v181
	v_lshlrev_b32_e32 v178, 16, v173
	v_and_b32_e32 v173, 0xffff0000, v173
	v_lshlrev_b32_e32 v179, 16, v177
	v_and_b32_e32 v177, 0xffff0000, v177
	v_mul_f32_e32 v4, 0xbfb8aa3b, v4
	v_mul_f32_e32 v5, 0xbfb8aa3b, v5
	v_mul_f32_e32 v180, 0xbfb8aa3b, v179
	v_mul_f32_e32 v181, 0xbfb8aa3b, v177
	v_exp_f32_e32 v4, v4
	v_exp_f32_e32 v5, v5
	v_exp_f32_e32 v180, v180
	v_exp_f32_e32 v181, v181
	v_add_f32_e32 v4, 1.0, v4
	v_add_f32_e32 v5, 1.0, v5
	v_add_f32_e32 v180, 1.0, v180
	v_add_f32_e32 v181, 1.0, v181
	v_rcp_f32_e32 v4, v4
	v_rcp_f32_e32 v5, v5
	v_rcp_f32_e32 v180, v180
	v_rcp_f32_e32 v181, v181
	v_mul_f32_e32 v4, v4, v178
	v_mul_f32_e32 v5, v5, v173
	v_mul_f32_e32 v180, v180, v179
	v_mul_f32_e32 v181, v181, v177
	v_mul_f32_e32 v4, v4, v180
	v_mul_f32_e32 v5, v5, v181
	v_cvt_pk_bf16_f32 v6, v6, v7
	v_cvt_pk_bf16_f32 v7, v8, v9
	v_cvt_pk_bf16_f32 v8, v2, v3
	v_cvt_pk_bf16_f32 v9, v4, v5
	global_store_dwordx4 v[146:147], v[6:9], off offset:256
	s_andn2_b64 vcc, exec, s[38:39]
	s_mov_b64 s[4:5], -1
	s_cbranch_vccnz .LBB0_686
	s_andn2_b64 vcc, exec, s[42:43]
	s_cbranch_vccnz .LBB0_685
	s_barrier
	s_branch .LBB0_685
	s_nop 0
	s_nop 0
	s_nop 0
	s_nop 0
	s_nop 0
	s_nop 0
